# GEMM K-loop MFMA order variant V1 (same-accumulator k-steps adjacent)
# speedup vs baseline: 1.0287x; 1.0287x over previous
; #define PG8_STAGE(bufoff, gbase, voff) do { _Pragma("unroll") for (int _i = 0; _i < 2; ++_i) \
;         __builtin_amdgcn_global_load_lds((const unsigned*)((const char*)(gbase) + (voff)[_i]), (PG8_LAS unsigned*)(lds + (bufoff) + ldsw + _i * 8192), 16, 0, 0); } while (0)
; #define PG8_LDA(dst, b, h) do { _Pragma("unroll") for (int m = 0; m < 4; ++m) _Pragma("unroll") for (int k = 0; k < 2; ++k) dst[m][k] = *(const PG8_LAS bf16x8*)(lds + PG8_SA(b, h) + aoff + m * 2048 + k * 1024); } while (0)
; #define PG8_LDB(dst, b, h) do { _Pragma("unroll") for (int n = 0; n < 2; ++n) _Pragma("unroll") for (int k = 0; k < 2; ++k) dst[n][k] = *(const PG8_LAS bf16x8*)(lds + PG8_SB(b, h) + boff + n * 2048 + k * 1024); } while (0)
; #define PG8_MMA(ai, bj, At, Bt) do { __builtin_amdgcn_s_setprio(1); _Pragma("unroll") for (int m = 0; m < 4; ++m) _Pragma("unroll") for (int n = 0; n < 2; ++n) _Pragma("unroll") for (int k = 0; k < 2; ++k) \
;         acc[ai][bj][m][n] = __builtin_amdgcn_mfma_f32_16x16x32_bf16(Bt[n][k], At[m][k], acc[ai][bj][m][n], 0, 0, 0); __builtin_amdgcn_s_setprio(0); } while (0)
; #define PG8_WAIT_V(n) asm volatile("s_waitcnt vmcnt(" #n ")" ::: "memory")
; #define PG8_WAIT_L(n) asm volatile("s_waitcnt lgkmcnt(" #n ")" ::: "memory")
; #define PG8_BAR __builtin_amdgcn_s_barrier()
; #define PG8_SCHED __builtin_amdgcn_sched_barrier(0)
; template <class Epi, class Sched, bool ALIGN_EPI = false, bool SP2 = false>
; __device__ __forceinline__ void gemm_phase(PG8_LAS unsigned char* lds, const Gemm g, const Sched& S, const Epi& E) {
;     ...
;             const bool last = (t == nt - 2);
;             const char* a1 = cA + (size_t)(t + 1) * kstep;
;             const char* a2 = last ? nA : cA + (size_t)(t + 2) * kstep; const char* b2 = last ? nB : cB + (size_t)(t + 2) * kstep;
;             const char* a3 = a2 + kstep; const char* b3 = b2 + kstep;
;             if (last && has_next) S.a_ready(nxt);
;             if constexpr (SP2) {
;             PG8_LDB(B0, 0, 0); PG8_LDB(B1, 0, 1); PG8_SCHED; PG8_LDA(At, 0, 0); PG8_STAGE(PG8_SA(1, 1), a1 + hstep, voffA);
;             PG8_WAIT_V(8); PG8_WAIT_L(0); PG8_BAR; PG8_MMA(0, 0, At, B0); PG8_MMA(0, 1, At, B1); PG8_BAR; PG8_SCHED;
;             PG8_LDA(At, 0, 1); PG8_STAGE(PG8_SB(0, 0), b2, voffB); PG8_STAGE(PG8_SB(0, 1), b2 + hstep, voffB); PG8_STAGE(PG8_SA(0, 0), a2, voffA);
.LBB0_132:
	s_add_u32 s18, s46, 0xfffc0080
	s_addc_u32 s38, s47, -1
	s_add_i32 s39, 0, 0x10000
	s_cmp_eq_u32 s85, 12
	s_cselect_b32 s81, s33, s38
	s_cselect_b32 s80, s73, s18
	v_add_u32_e32 v0, s39, v176
	s_cselect_b32 s45, s75, s84
	s_cselect_b32 s44, s82, s83
	s_add_i32 s18, 0, 0x14000
	ds_read_b128 v[144:147], v0
	ds_read_b128 v[148:151], v0 offset:1024
	ds_read_b128 v[152:155], v0 offset:2048
	ds_read_b128 v[156:159], v0 offset:3072
	v_add_u32_e32 v0, s18, v176
	ds_read_b128 v[160:163], v0
	ds_read_b128 v[164:167], v0 offset:1024
	ds_read_b128 v[168:171], v0 offset:2048
	ds_read_b128 v[172:175], v0 offset:3072
	v_lshl_add_u64 v[218:219], s[46:47], 0, v[140:141]
	s_add_i32 m0, s92, 0xc000
	ds_read_b128 v[180:183], v178
	ds_read_b128 v[184:187], v178 offset:1024
	ds_read_b128 v[188:191], v178 offset:2048
	ds_read_b128 v[192:195], v178 offset:3072
	ds_read_b128 v[202:205], v178 offset:4096
	ds_read_b128 v[206:209], v178 offset:5120
	ds_read_b128 v[210:213], v178 offset:6144
	ds_read_b128 v[214:217], v178 offset:7168
	global_load_lds_dwordx4 v[218:219], off
	v_lshl_add_u64 v[218:219], s[46:47], 0, v[142:143]
	s_add_i32 m0, s92, 0xe000
	s_nop 0
	global_load_lds_dwordx4 v[218:219], off
	s_waitcnt vmcnt(8)
	s_waitcnt lgkmcnt(0)
	s_barrier
	s_setprio 1
	s_waitcnt lgkmcnt(0)
	v_mfma_f32_16x16x32_bf16 v[118:121], v[144:147], v[180:183], v[118:121]
	v_mfma_f32_16x16x32_bf16 v[118:121], v[148:151], v[184:187], v[118:121]
	v_mfma_f32_16x16x32_bf16 v[102:105], v[144:147], v[188:191], v[102:105]
	v_mfma_f32_16x16x32_bf16 v[102:105], v[148:151], v[192:195], v[102:105]
	v_mfma_f32_16x16x32_bf16 v[86:89], v[144:147], v[202:205], v[86:89]
	v_mfma_f32_16x16x32_bf16 v[86:89], v[148:151], v[206:209], v[86:89]
	v_mfma_f32_16x16x32_bf16 v[70:73], v[144:147], v[210:213], v[70:73]
	v_mfma_f32_16x16x32_bf16 v[70:73], v[148:151], v[214:217], v[70:73]
	v_mfma_f32_16x16x32_bf16 v[114:117], v[152:155], v[180:183], v[114:117]
	v_mfma_f32_16x16x32_bf16 v[114:117], v[156:159], v[184:187], v[114:117]
	v_mfma_f32_16x16x32_bf16 v[98:101], v[152:155], v[188:191], v[98:101]
	v_mfma_f32_16x16x32_bf16 v[98:101], v[156:159], v[192:195], v[98:101]
	v_mfma_f32_16x16x32_bf16 v[82:85], v[152:155], v[202:205], v[82:85]
	v_mfma_f32_16x16x32_bf16 v[82:85], v[156:159], v[206:209], v[82:85]
	v_mfma_f32_16x16x32_bf16 v[66:69], v[152:155], v[210:213], v[66:69]
	v_mfma_f32_16x16x32_bf16 v[66:69], v[156:159], v[214:217], v[66:69]
	s_setprio 0
	s_setprio 1
	v_mfma_f32_16x16x32_bf16 v[126:129], v[160:163], v[180:183], v[126:129]
	v_mfma_f32_16x16x32_bf16 v[126:129], v[164:167], v[184:187], v[126:129]
	v_mfma_f32_16x16x32_bf16 v[110:113], v[160:163], v[188:191], v[110:113]
	v_mfma_f32_16x16x32_bf16 v[110:113], v[164:167], v[192:195], v[110:113]
	v_mfma_f32_16x16x32_bf16 v[94:97], v[160:163], v[202:205], v[94:97]
	v_mfma_f32_16x16x32_bf16 v[94:97], v[164:167], v[206:209], v[94:97]
	v_mfma_f32_16x16x32_bf16 v[78:81], v[160:163], v[210:213], v[78:81]
	v_mfma_f32_16x16x32_bf16 v[78:81], v[164:167], v[214:217], v[78:81]
	v_mfma_f32_16x16x32_bf16 v[122:125], v[168:171], v[180:183], v[122:125]
	v_mfma_f32_16x16x32_bf16 v[122:125], v[172:175], v[184:187], v[122:125]
	v_mfma_f32_16x16x32_bf16 v[106:109], v[168:171], v[188:191], v[106:109]
	v_mfma_f32_16x16x32_bf16 v[106:109], v[172:175], v[192:195], v[106:109]
	v_mfma_f32_16x16x32_bf16 v[90:93], v[168:171], v[202:205], v[90:93]
	v_mfma_f32_16x16x32_bf16 v[90:93], v[172:175], v[206:209], v[90:93]
	v_mfma_f32_16x16x32_bf16 v[74:77], v[168:171], v[210:213], v[74:77]
	v_mfma_f32_16x16x32_bf16 v[74:77], v[172:175], v[214:217], v[74:77]
	s_setprio 0
	s_barrier
	s_add_i32 s38, s39, s91
	v_lshl_add_u64 v[218:219], s[44:45], 0, v[134:135]
	s_mov_b32 m0, s38
	ds_read_b128 v[180:183], v178 offset:16384
	ds_read_b128 v[184:187], v178 offset:17408
	ds_read_b128 v[188:191], v178 offset:18432
	ds_read_b128 v[192:195], v178 offset:19456
	ds_read_b128 v[202:205], v178 offset:20480
	ds_read_b128 v[206:209], v178 offset:21504
	ds_read_b128 v[210:213], v178 offset:22528
	ds_read_b128 v[214:217], v178 offset:23552
	global_load_lds_dwordx4 v[218:219], off
	s_add_i32 m0, s38, 0x2000
	s_add_u32 s38, s44, 0x40000
	v_lshl_add_u64 v[220:221], s[44:45], 0, v[130:131]
	s_addc_u32 s39, s45, 0
	s_add_i32 s18, s18, s91
	global_load_lds_dwordx4 v[220:221], off
	v_lshl_add_u64 v[222:223], s[38:39], 0, v[134:135]
	s_mov_b32 m0, s18
	v_lshl_add_u64 v[224:225], s[80:81], 0, v[132:133]
	global_load_lds_dwordx4 v[222:223], off
	v_lshl_add_u64 v[222:223], s[38:39], 0, v[130:131]
	s_add_i32 m0, s18, 0x2000
	s_nop 0
	global_load_lds_dwordx4 v[222:223], off
	v_lshl_add_u64 v[222:223], s[80:81], 0, v[136:137]
	s_mov_b32 m0, s92
	s_nop 0
	global_load_lds_dwordx4 v[222:223], off
	s_mov_b32 m0, s93
	s_nop 0
	global_load_lds_dwordx4 v[224:225], off
	s_waitcnt vmcnt(8)
	s_waitcnt lgkmcnt(0)
	s_barrier
; #define PG8_STAGE(bufoff, gbase, voff) do { _Pragma("unroll") for (int _i = 0; _i < 2; ++_i) \
;         __builtin_amdgcn_global_load_lds((const unsigned*)((const char*)(gbase) + (voff)[_i]), (PG8_LAS unsigned*)(lds + (bufoff) + ldsw + _i * 8192), 16, 0, 0); } while (0)
; #define PG8_LDA(dst, b, h) do { _Pragma("unroll") for (int m = 0; m < 4; ++m) _Pragma("unroll") for (int k = 0; k < 2; ++k) dst[m][k] = *(const PG8_LAS bf16x8*)(lds + PG8_SA(b, h) + aoff + m * 2048 + k * 1024); } while (0)
; #define PG8_LDB(dst, b, h) do { _Pragma("unroll") for (int n = 0; n < 2; ++n) _Pragma("unroll") for (int k = 0; k < 2; ++k) dst[n][k] = *(const PG8_LAS bf16x8*)(lds + PG8_SB(b, h) + boff + n * 2048 + k * 1024); } while (0)
; #define PG8_MMA(ai, bj, At, Bt) do { __builtin_amdgcn_s_setprio(1); _Pragma("unroll") for (int m = 0; m < 4; ++m) _Pragma("unroll") for (int n = 0; n < 2; ++n) _Pragma("unroll") for (int k = 0; k < 2; ++k) \
;         acc[ai][bj][m][n] = __builtin_amdgcn_mfma_f32_16x16x32_bf16(Bt[n][k], At[m][k], acc[ai][bj][m][n], 0, 0, 0); __builtin_amdgcn_s_setprio(0); } while (0)
; #define PG8_WAIT_V(n) asm volatile("s_waitcnt vmcnt(" #n ")" ::: "memory")
; #define PG8_WAIT_L(n) asm volatile("s_waitcnt lgkmcnt(" #n ")" ::: "memory")
; #define PG8_BAR __builtin_amdgcn_s_barrier()
; #define PG8_SCHED __builtin_amdgcn_sched_barrier(0)
; template <class Epi, class Sched, bool ALIGN_EPI = false, bool SP2 = false>
; __device__ __forceinline__ void gemm_phase(PG8_LAS unsigned char* lds, const Gemm g, const Sched& S, const Epi& E) {
;     ...
;             PG8_WAIT_V(8); PG8_WAIT_L(0); PG8_BAR; PG8_MMA(1, 0, At, B0); PG8_MMA(1, 1, At, B1); PG8_BAR; PG8_SCHED;
;             PG8_LDB(B0, 1, 0); PG8_LDB(B1, 1, 1); PG8_SCHED; PG8_LDA(At, 1, 0); PG8_STAGE(PG8_SA(0, 1), a2 + hstep, voffA);
;             PG8_WAIT_V(8); PG8_WAIT_L(0); PG8_BAR; PG8_MMA(0, 0, At, B0); PG8_MMA(0, 1, At, B1); PG8_BAR; PG8_SCHED;
	s_setprio 1
	s_waitcnt lgkmcnt(0)
	v_mfma_f32_16x16x32_bf16 v[54:57], v[144:147], v[180:183], v[54:57]
	v_mfma_f32_16x16x32_bf16 v[54:57], v[148:151], v[184:187], v[54:57]
	v_mfma_f32_16x16x32_bf16 v[38:41], v[144:147], v[188:191], v[38:41]
	v_mfma_f32_16x16x32_bf16 v[38:41], v[148:151], v[192:195], v[38:41]
	v_mfma_f32_16x16x32_bf16 v[22:25], v[144:147], v[202:205], v[22:25]
	v_mfma_f32_16x16x32_bf16 v[22:25], v[148:151], v[206:209], v[22:25]
	v_mfma_f32_16x16x32_bf16 v[6:9], v[144:147], v[210:213], v[6:9]
	v_mfma_f32_16x16x32_bf16 v[6:9], v[148:151], v[214:217], v[6:9]
	v_mfma_f32_16x16x32_bf16 v[50:53], v[152:155], v[180:183], v[50:53]
	v_mfma_f32_16x16x32_bf16 v[50:53], v[156:159], v[184:187], v[50:53]
	v_mfma_f32_16x16x32_bf16 v[34:37], v[152:155], v[188:191], v[34:37]
	v_mfma_f32_16x16x32_bf16 v[34:37], v[156:159], v[192:195], v[34:37]
	v_mfma_f32_16x16x32_bf16 v[18:21], v[152:155], v[202:205], v[18:21]
	v_mfma_f32_16x16x32_bf16 v[18:21], v[156:159], v[206:209], v[18:21]
	v_mfma_f32_16x16x32_bf16 v[2:5], v[152:155], v[210:213], v[2:5]
	v_mfma_f32_16x16x32_bf16 v[2:5], v[156:159], v[214:217], v[2:5]
	s_setprio 0
	s_setprio 1
	v_mfma_f32_16x16x32_bf16 v[62:65], v[160:163], v[180:183], v[62:65]
	v_mfma_f32_16x16x32_bf16 v[62:65], v[164:167], v[184:187], v[62:65]
	v_mfma_f32_16x16x32_bf16 v[46:49], v[160:163], v[188:191], v[46:49]
	v_mfma_f32_16x16x32_bf16 v[46:49], v[164:167], v[192:195], v[46:49]
	v_mfma_f32_16x16x32_bf16 v[30:33], v[160:163], v[202:205], v[30:33]
	v_mfma_f32_16x16x32_bf16 v[30:33], v[164:167], v[206:209], v[30:33]
	v_mfma_f32_16x16x32_bf16 v[10:13], v[160:163], v[210:213], v[10:13]
	v_mfma_f32_16x16x32_bf16 v[10:13], v[164:167], v[214:217], v[10:13]
	v_mfma_f32_16x16x32_bf16 v[58:61], v[168:171], v[180:183], v[58:61]
	v_mfma_f32_16x16x32_bf16 v[58:61], v[172:175], v[184:187], v[58:61]
	v_mfma_f32_16x16x32_bf16 v[42:45], v[168:171], v[188:191], v[42:45]
	v_mfma_f32_16x16x32_bf16 v[42:45], v[172:175], v[192:195], v[42:45]
	v_mfma_f32_16x16x32_bf16 v[26:29], v[168:171], v[202:205], v[26:29]
	v_mfma_f32_16x16x32_bf16 v[26:29], v[172:175], v[206:209], v[26:29]
	v_mfma_f32_16x16x32_bf16 v[14:17], v[168:171], v[210:213], v[14:17]
	v_mfma_f32_16x16x32_bf16 v[14:17], v[172:175], v[214:217], v[14:17]
	s_setprio 0
	s_barrier
	s_add_i32 s18, 0, 0x18000
	v_add_u32_e32 v0, s18, v176
	s_add_i32 vcc_lo, 0, 0x1c000
	ds_read_b128 v[144:147], v0
	ds_read_b128 v[148:151], v0 offset:1024
	ds_read_b128 v[152:155], v0 offset:2048
	ds_read_b128 v[156:159], v0 offset:3072
	v_add_u32_e32 v0, vcc_lo, v176
	ds_read_b128 v[160:163], v0
	ds_read_b128 v[164:167], v0 offset:1024
	ds_read_b128 v[168:171], v0 offset:2048
	ds_read_b128 v[172:175], v0 offset:3072
	s_add_u32 s38, s80, 0x40000
	s_addc_u32 s39, s81, 0
	s_mov_b32 m0, s94
	v_lshl_add_u64 v[226:227], s[38:39], 0, v[136:137]
	ds_read_b128 v[180:183], v178 offset:32768
	ds_read_b128 v[184:187], v178 offset:33792
	ds_read_b128 v[188:191], v178 offset:34816
	ds_read_b128 v[192:195], v178 offset:35840
	ds_read_b128 v[202:205], v178 offset:36864
	ds_read_b128 v[206:209], v178 offset:37888
	ds_read_b128 v[210:213], v178 offset:38912
	ds_read_b128 v[214:217], v178 offset:39936
	global_load_lds_dwordx4 v[226:227], off
	v_lshl_add_u64 v[226:227], s[38:39], 0, v[132:133]
	s_mov_b32 m0, s95
	s_nop 0
	global_load_lds_dwordx4 v[226:227], off
	s_waitcnt vmcnt(8)
	s_waitcnt lgkmcnt(0)
	s_barrier
	s_setprio 1
	s_waitcnt lgkmcnt(0)
	v_mfma_f32_16x16x32_bf16 v[118:121], v[144:147], v[180:183], v[118:121]
	v_mfma_f32_16x16x32_bf16 v[118:121], v[148:151], v[184:187], v[118:121]
	v_mfma_f32_16x16x32_bf16 v[102:105], v[144:147], v[188:191], v[102:105]
	v_mfma_f32_16x16x32_bf16 v[102:105], v[148:151], v[192:195], v[102:105]
	v_mfma_f32_16x16x32_bf16 v[86:89], v[144:147], v[202:205], v[86:89]
	v_mfma_f32_16x16x32_bf16 v[86:89], v[148:151], v[206:209], v[86:89]
	v_mfma_f32_16x16x32_bf16 v[70:73], v[144:147], v[210:213], v[70:73]
	v_mfma_f32_16x16x32_bf16 v[70:73], v[148:151], v[214:217], v[70:73]
	v_mfma_f32_16x16x32_bf16 v[114:117], v[152:155], v[180:183], v[114:117]
	v_mfma_f32_16x16x32_bf16 v[114:117], v[156:159], v[184:187], v[114:117]
	v_mfma_f32_16x16x32_bf16 v[98:101], v[152:155], v[188:191], v[98:101]
	v_mfma_f32_16x16x32_bf16 v[98:101], v[156:159], v[192:195], v[98:101]
	v_mfma_f32_16x16x32_bf16 v[82:85], v[152:155], v[202:205], v[82:85]
	v_mfma_f32_16x16x32_bf16 v[82:85], v[156:159], v[206:209], v[82:85]
	v_mfma_f32_16x16x32_bf16 v[66:69], v[152:155], v[210:213], v[66:69]
	v_mfma_f32_16x16x32_bf16 v[66:69], v[156:159], v[214:217], v[66:69]
	s_setprio 0
	s_setprio 1
	v_mfma_f32_16x16x32_bf16 v[126:129], v[160:163], v[180:183], v[126:129]
	v_mfma_f32_16x16x32_bf16 v[126:129], v[164:167], v[184:187], v[126:129]
	v_mfma_f32_16x16x32_bf16 v[110:113], v[160:163], v[188:191], v[110:113]
	v_mfma_f32_16x16x32_bf16 v[110:113], v[164:167], v[192:195], v[110:113]
	v_mfma_f32_16x16x32_bf16 v[94:97], v[160:163], v[202:205], v[94:97]
	v_mfma_f32_16x16x32_bf16 v[94:97], v[164:167], v[206:209], v[94:97]
	v_mfma_f32_16x16x32_bf16 v[78:81], v[160:163], v[210:213], v[78:81]
	v_mfma_f32_16x16x32_bf16 v[78:81], v[164:167], v[214:217], v[78:81]
	v_mfma_f32_16x16x32_bf16 v[122:125], v[168:171], v[180:183], v[122:125]
	v_mfma_f32_16x16x32_bf16 v[122:125], v[172:175], v[184:187], v[122:125]
	v_mfma_f32_16x16x32_bf16 v[106:109], v[168:171], v[188:191], v[106:109]
	v_mfma_f32_16x16x32_bf16 v[106:109], v[172:175], v[192:195], v[106:109]
	v_mfma_f32_16x16x32_bf16 v[90:93], v[168:171], v[202:205], v[90:93]
	v_mfma_f32_16x16x32_bf16 v[90:93], v[172:175], v[206:209], v[90:93]
	v_mfma_f32_16x16x32_bf16 v[74:77], v[168:171], v[210:213], v[74:77]
	v_mfma_f32_16x16x32_bf16 v[74:77], v[172:175], v[214:217], v[74:77]
	s_setprio 0
	s_barrier
; #define PG8_STAGE(bufoff, gbase, voff) do { _Pragma("unroll") for (int _i = 0; _i < 2; ++_i) \
;         __builtin_amdgcn_global_load_lds((const unsigned*)((const char*)(gbase) + (voff)[_i]), (PG8_LAS unsigned*)(lds + (bufoff) + ldsw + _i * 8192), 16, 0, 0); } while (0)
; #define PG8_LDA(dst, b, h) do { _Pragma("unroll") for (int m = 0; m < 4; ++m) _Pragma("unroll") for (int k = 0; k < 2; ++k) dst[m][k] = *(const PG8_LAS bf16x8*)(lds + PG8_SA(b, h) + aoff + m * 2048 + k * 1024); } while (0)
; #define PG8_MMA(ai, bj, At, Bt) do { __builtin_amdgcn_s_setprio(1); _Pragma("unroll") for (int m = 0; m < 4; ++m) _Pragma("unroll") for (int n = 0; n < 2; ++n) _Pragma("unroll") for (int k = 0; k < 2; ++k) \
;         acc[ai][bj][m][n] = __builtin_amdgcn_mfma_f32_16x16x32_bf16(Bt[n][k], At[m][k], acc[ai][bj][m][n], 0, 0, 0); __builtin_amdgcn_s_setprio(0); } while (0)
; #define PG8_WAIT_V(n) asm volatile("s_waitcnt vmcnt(" #n ")" ::: "memory")
; #define PG8_WAIT_L(n) asm volatile("s_waitcnt lgkmcnt(" #n ")" ::: "memory")
; #define PG8_BAR __builtin_amdgcn_s_barrier()
; #define PG8_SCHED __builtin_amdgcn_sched_barrier(0)
; template <class Epi, class Sched, bool ALIGN_EPI = false, bool SP2 = false>
; __device__ __forceinline__ void gemm_phase(PG8_LAS unsigned char* lds, const Gemm g, const Sched& S, const Epi& E) {
;     ...
;             PG8_LDA(At, 1, 1); PG8_STAGE(PG8_SB(1, 0), b3, voffB); PG8_STAGE(PG8_SB(1, 1), b3 + hstep, voffB); PG8_STAGE(PG8_SA(1, 0), a3, voffA);
;             PG8_WAIT_V(8); PG8_WAIT_L(0); PG8_BAR; PG8_MMA(1, 0, At, B0); PG8_MMA(1, 1, At, B1); PG8_BAR; PG8_SCHED;
	s_add_i32 s18, s18, s91
	v_lshl_add_u64 v[218:219], v[218:219], 0, s[30:31]
	s_mov_b32 m0, s18
	ds_read_b128 v[180:183], v178 offset:49152
	ds_read_b128 v[184:187], v178 offset:50176
	ds_read_b128 v[188:191], v178 offset:51200
	ds_read_b128 v[192:195], v178 offset:52224
	ds_read_b128 v[202:205], v178 offset:53248
	ds_read_b128 v[206:209], v178 offset:54272
	ds_read_b128 v[210:213], v178 offset:55296
	ds_read_b128 v[214:217], v178 offset:56320
	global_load_lds_dwordx4 v[218:219], off
	s_add_i32 m0, s18, 0x2000
	s_add_u32 s38, s44, 0x40080
	v_lshl_add_u64 v[218:219], v[220:221], 0, s[30:31]
	s_addc_u32 s39, s45, 0
	s_add_i32 s18, vcc_lo, s91
	global_load_lds_dwordx4 v[218:219], off
	v_lshl_add_u64 v[218:219], s[38:39], 0, v[134:135]
	s_mov_b32 m0, s18
	s_nop 0
	global_load_lds_dwordx4 v[218:219], off
	v_lshl_add_u64 v[218:219], s[38:39], 0, v[130:131]
	s_add_i32 m0, s18, 0x2000
	s_nop 0
	global_load_lds_dwordx4 v[218:219], off
	v_lshl_add_u64 v[218:219], v[222:223], 0, s[30:31]
	s_mov_b32 m0, s7
	s_nop 0
	global_load_lds_dwordx4 v[218:219], off
	v_lshl_add_u64 v[218:219], v[224:225], 0, s[30:31]
	s_mov_b32 m0, s96
	s_nop 0
	global_load_lds_dwordx4 v[218:219], off
	s_waitcnt vmcnt(8)
	s_waitcnt lgkmcnt(0)
	s_barrier
	s_setprio 1
	s_waitcnt lgkmcnt(0)
	v_mfma_f32_16x16x32_bf16 v[54:57], v[144:147], v[180:183], v[54:57]
	v_mfma_f32_16x16x32_bf16 v[54:57], v[148:151], v[184:187], v[54:57]
	v_mfma_f32_16x16x32_bf16 v[38:41], v[144:147], v[188:191], v[38:41]
	v_mfma_f32_16x16x32_bf16 v[38:41], v[148:151], v[192:195], v[38:41]
	v_mfma_f32_16x16x32_bf16 v[22:25], v[144:147], v[202:205], v[22:25]
	v_mfma_f32_16x16x32_bf16 v[22:25], v[148:151], v[206:209], v[22:25]
	v_mfma_f32_16x16x32_bf16 v[6:9], v[144:147], v[210:213], v[6:9]
	v_mfma_f32_16x16x32_bf16 v[6:9], v[148:151], v[214:217], v[6:9]
	v_mfma_f32_16x16x32_bf16 v[50:53], v[152:155], v[180:183], v[50:53]
	v_mfma_f32_16x16x32_bf16 v[50:53], v[156:159], v[184:187], v[50:53]
	v_mfma_f32_16x16x32_bf16 v[34:37], v[152:155], v[188:191], v[34:37]
	v_mfma_f32_16x16x32_bf16 v[34:37], v[156:159], v[192:195], v[34:37]
	v_mfma_f32_16x16x32_bf16 v[18:21], v[152:155], v[202:205], v[18:21]
	v_mfma_f32_16x16x32_bf16 v[18:21], v[156:159], v[206:209], v[18:21]
	v_mfma_f32_16x16x32_bf16 v[2:5], v[152:155], v[210:213], v[2:5]
	v_mfma_f32_16x16x32_bf16 v[2:5], v[156:159], v[214:217], v[2:5]
	s_setprio 0
	s_setprio 1
	v_mfma_f32_16x16x32_bf16 v[62:65], v[160:163], v[180:183], v[62:65]
	v_mfma_f32_16x16x32_bf16 v[62:65], v[164:167], v[184:187], v[62:65]
	v_mfma_f32_16x16x32_bf16 v[46:49], v[160:163], v[188:191], v[46:49]
	v_mfma_f32_16x16x32_bf16 v[46:49], v[164:167], v[192:195], v[46:49]
	v_mfma_f32_16x16x32_bf16 v[30:33], v[160:163], v[202:205], v[30:33]
	v_mfma_f32_16x16x32_bf16 v[30:33], v[164:167], v[206:209], v[30:33]
	v_mfma_f32_16x16x32_bf16 v[10:13], v[160:163], v[210:213], v[10:13]
	v_mfma_f32_16x16x32_bf16 v[10:13], v[164:167], v[214:217], v[10:13]
	v_mfma_f32_16x16x32_bf16 v[58:61], v[168:171], v[180:183], v[58:61]
	v_mfma_f32_16x16x32_bf16 v[58:61], v[172:175], v[184:187], v[58:61]
	v_mfma_f32_16x16x32_bf16 v[42:45], v[168:171], v[188:191], v[42:45]
	v_mfma_f32_16x16x32_bf16 v[42:45], v[172:175], v[192:195], v[42:45]
	v_mfma_f32_16x16x32_bf16 v[26:29], v[168:171], v[202:205], v[26:29]
	v_mfma_f32_16x16x32_bf16 v[26:29], v[172:175], v[206:209], v[26:29]
	v_mfma_f32_16x16x32_bf16 v[14:17], v[168:171], v[210:213], v[14:17]
	v_mfma_f32_16x16x32_bf16 v[14:17], v[172:175], v[214:217], v[14:17]
	s_setprio 0
	s_barrier
	s_add_i32 s85, s85, 2
	s_add_u32 s46, s46, 0x100
	s_addc_u32 s47, s47, 0
	s_add_u32 s83, s83, 0x100
	s_addc_u32 s84, s84, 0
	s_cmp_gt_u32 s85, 13
	s_cbranch_scc0 .LBB0_132
	s_and_b64 vcc, exec, s[10:11]
	s_cbranch_vccz .LBB0_135
	s_barrier

; #define PG8_STAGE(bufoff, gbase, voff) do { _Pragma("unroll") for (int _i = 0; _i < 2; ++_i) \
;         __builtin_amdgcn_global_load_lds((const unsigned*)((const char*)(gbase) + (voff)[_i]), (PG8_LAS unsigned*)(lds + (bufoff) + ldsw + _i * 8192), 16, 0, 0); } while (0)
; #define PG8_LDA(dst, b, h) do { _Pragma("unroll") for (int m = 0; m < 4; ++m) _Pragma("unroll") for (int k = 0; k < 2; ++k) dst[m][k] = *(const PG8_LAS bf16x8*)(lds + PG8_SA(b, h) + aoff + m * 2048 + k * 1024); } while (0)
; #define PG8_LDB(dst, b, h) do { _Pragma("unroll") for (int n = 0; n < 2; ++n) _Pragma("unroll") for (int k = 0; k < 2; ++k) dst[n][k] = *(const PG8_LAS bf16x8*)(lds + PG8_SB(b, h) + boff + n * 2048 + k * 1024); } while (0)
; #define PG8_MMA(ai, bj, At, Bt) do { __builtin_amdgcn_s_setprio(1); _Pragma("unroll") for (int m = 0; m < 4; ++m) _Pragma("unroll") for (int n = 0; n < 2; ++n) _Pragma("unroll") for (int k = 0; k < 2; ++k) \
;         acc[ai][bj][m][n] = __builtin_amdgcn_mfma_f32_16x16x32_bf16(Bt[n][k], At[m][k], acc[ai][bj][m][n], 0, 0, 0); __builtin_amdgcn_s_setprio(0); } while (0)
; #define PG8_WAIT_V(n) asm volatile("s_waitcnt vmcnt(" #n ")" ::: "memory")
; #define PG8_WAIT_L(n) asm volatile("s_waitcnt lgkmcnt(" #n ")" ::: "memory")
; #define PG8_BAR __builtin_amdgcn_s_barrier()
; #define PG8_SCHED __builtin_amdgcn_sched_barrier(0)
; template <class Epi, class Sched, bool ALIGN_EPI = false, bool SP2 = false>
; __device__ __forceinline__ void gemm_phase(PG8_LAS unsigned char* lds, const Gemm g, const Sched& S, const Epi& E) {
;     ...
;             const bool last = (t == nt - 2);
;             const char* a1 = cA + (size_t)(t + 1) * kstep;
;             const char* a2 = last ? nA : cA + (size_t)(t + 2) * kstep; const char* b2 = last ? nB : cB + (size_t)(t + 2) * kstep;
;             const char* a3 = a2 + kstep; const char* b3 = b2 + kstep;
;             if (last && has_next) S.a_ready(nxt);
;             if constexpr (SP2) {
;             PG8_LDB(B0, 0, 0); PG8_LDB(B1, 0, 1); PG8_SCHED; PG8_LDA(At, 0, 0); PG8_STAGE(PG8_SA(1, 1), a1 + hstep, voffA);
;             PG8_WAIT_V(8); PG8_WAIT_L(0); PG8_BAR; PG8_MMA(0, 0, At, B0); PG8_MMA(0, 1, At, B1); PG8_BAR; PG8_SCHED;
;             PG8_LDA(At, 0, 1); PG8_STAGE(PG8_SB(0, 0), b2, voffB); PG8_STAGE(PG8_SB(0, 1), b2 + hstep, voffB); PG8_STAGE(PG8_SA(0, 0), a2, voffA);
.LBB0_220:
	s_add_u32 s18, s60, 0xfffc0080
	s_addc_u32 s38, s61, -1
	s_add_i32 s39, 0, 0x10000
	s_cmp_eq_u32 s82, 12
	s_cselect_b32 s65, s47, s38
	s_cselect_b32 s64, s78, s18
	v_add_u32_e32 v145, s39, v141
	s_cselect_b32 s57, s49, s81
	s_cselect_b32 s56, s79, s80
	s_add_i32 s18, 0, 0x14000
	ds_read_b128 v[146:149], v145
	ds_read_b128 v[150:153], v145 offset:1024
	ds_read_b128 v[154:157], v145 offset:2048
	ds_read_b128 v[158:161], v145 offset:3072
	v_add_u32_e32 v145, s18, v141
	ds_read_b128 v[162:165], v145
	ds_read_b128 v[166:169], v145 offset:1024
	ds_read_b128 v[170:173], v145 offset:2048
	ds_read_b128 v[174:177], v145 offset:3072
	v_lshl_add_u64 v[194:195], s[60:61], 0, v[136:137]
	s_add_i32 m0, s29, 0xc000
	ds_read_b128 v[178:181], v144
	ds_read_b128 v[182:185], v144 offset:1024
	ds_read_b128 v[186:189], v144 offset:2048
	ds_read_b128 v[190:193], v144 offset:3072
	ds_read_b128 v[202:205], v144 offset:4096
	ds_read_b128 v[206:209], v144 offset:5120
	ds_read_b128 v[210:213], v144 offset:6144
	ds_read_b128 v[214:217], v144 offset:7168
	global_load_lds_dwordx4 v[194:195], off
	v_lshl_add_u64 v[194:195], s[60:61], 0, v[138:139]
	s_add_i32 m0, s29, 0xe000
	s_nop 0
	global_load_lds_dwordx4 v[194:195], off
	s_waitcnt vmcnt(8)
	s_waitcnt lgkmcnt(0)
	s_barrier
	s_setprio 1
	s_waitcnt lgkmcnt(0)
	v_mfma_f32_16x16x32_bf16 v[114:117], v[146:149], v[178:181], v[114:117]
	v_mfma_f32_16x16x32_bf16 v[114:117], v[150:153], v[182:185], v[114:117]
	v_mfma_f32_16x16x32_bf16 v[98:101], v[146:149], v[186:189], v[98:101]
	v_mfma_f32_16x16x32_bf16 v[98:101], v[150:153], v[190:193], v[98:101]
	v_mfma_f32_16x16x32_bf16 v[82:85], v[146:149], v[202:205], v[82:85]
	v_mfma_f32_16x16x32_bf16 v[82:85], v[150:153], v[206:209], v[82:85]
	v_mfma_f32_16x16x32_bf16 v[66:69], v[146:149], v[210:213], v[66:69]
	v_mfma_f32_16x16x32_bf16 v[66:69], v[150:153], v[214:217], v[66:69]
	v_mfma_f32_16x16x32_bf16 v[118:121], v[154:157], v[178:181], v[118:121]
	v_mfma_f32_16x16x32_bf16 v[118:121], v[158:161], v[182:185], v[118:121]
	v_mfma_f32_16x16x32_bf16 v[102:105], v[154:157], v[186:189], v[102:105]
	v_mfma_f32_16x16x32_bf16 v[102:105], v[158:161], v[190:193], v[102:105]
	v_mfma_f32_16x16x32_bf16 v[86:89], v[154:157], v[202:205], v[86:89]
	v_mfma_f32_16x16x32_bf16 v[86:89], v[158:161], v[206:209], v[86:89]
	v_mfma_f32_16x16x32_bf16 v[70:73], v[154:157], v[210:213], v[70:73]
	v_mfma_f32_16x16x32_bf16 v[70:73], v[158:161], v[214:217], v[70:73]
	s_setprio 0
	s_setprio 1
	v_mfma_f32_16x16x32_bf16 v[122:125], v[162:165], v[178:181], v[122:125]
	v_mfma_f32_16x16x32_bf16 v[122:125], v[166:169], v[182:185], v[122:125]
	v_mfma_f32_16x16x32_bf16 v[106:109], v[162:165], v[186:189], v[106:109]
	v_mfma_f32_16x16x32_bf16 v[106:109], v[166:169], v[190:193], v[106:109]
	v_mfma_f32_16x16x32_bf16 v[90:93], v[162:165], v[202:205], v[90:93]
	v_mfma_f32_16x16x32_bf16 v[90:93], v[166:169], v[206:209], v[90:93]
	v_mfma_f32_16x16x32_bf16 v[74:77], v[162:165], v[210:213], v[74:77]
	v_mfma_f32_16x16x32_bf16 v[74:77], v[166:169], v[214:217], v[74:77]
	v_mfma_f32_16x16x32_bf16 v[126:129], v[170:173], v[178:181], v[126:129]
	v_mfma_f32_16x16x32_bf16 v[126:129], v[174:177], v[182:185], v[126:129]
	v_mfma_f32_16x16x32_bf16 v[110:113], v[170:173], v[186:189], v[110:113]
	v_mfma_f32_16x16x32_bf16 v[110:113], v[174:177], v[190:193], v[110:113]
	v_mfma_f32_16x16x32_bf16 v[94:97], v[170:173], v[202:205], v[94:97]
	v_mfma_f32_16x16x32_bf16 v[94:97], v[174:177], v[206:209], v[94:97]
	v_mfma_f32_16x16x32_bf16 v[78:81], v[170:173], v[210:213], v[78:81]
	v_mfma_f32_16x16x32_bf16 v[78:81], v[174:177], v[214:217], v[78:81]
	s_setprio 0
	s_barrier
	s_add_i32 s38, s39, s27
	v_lshl_add_u64 v[194:195], s[56:57], 0, v[0:1]
	s_mov_b32 m0, s38
	ds_read_b128 v[178:181], v144 offset:16384
	ds_read_b128 v[182:185], v144 offset:17408
	ds_read_b128 v[186:189], v144 offset:18432
	ds_read_b128 v[190:193], v144 offset:19456
	ds_read_b128 v[202:205], v144 offset:20480
	ds_read_b128 v[206:209], v144 offset:21504
	ds_read_b128 v[210:213], v144 offset:22528
	ds_read_b128 v[214:217], v144 offset:23552
	global_load_lds_dwordx4 v[194:195], off
	s_add_i32 m0, s38, 0x2000
	s_add_u32 s38, s56, 0x40000
	v_lshl_add_u64 v[218:219], s[56:57], 0, v[130:131]
	s_addc_u32 s39, s57, 0
	s_add_i32 s18, s18, s27
	global_load_lds_dwordx4 v[218:219], off
	v_lshl_add_u64 v[220:221], s[38:39], 0, v[0:1]
	s_mov_b32 m0, s18
	v_lshl_add_u64 v[222:223], s[64:65], 0, v[132:133]
	global_load_lds_dwordx4 v[220:221], off
	v_lshl_add_u64 v[220:221], s[38:39], 0, v[130:131]
	s_add_i32 m0, s18, 0x2000
	s_nop 0
	global_load_lds_dwordx4 v[220:221], off
	v_lshl_add_u64 v[220:221], s[64:65], 0, v[134:135]
	s_mov_b32 m0, s29
	s_nop 0
	global_load_lds_dwordx4 v[220:221], off
	s_mov_b32 m0, s33
	s_nop 0
	global_load_lds_dwordx4 v[222:223], off
	s_waitcnt vmcnt(8)
	s_waitcnt lgkmcnt(0)
	s_barrier
; #define PG8_STAGE(bufoff, gbase, voff) do { _Pragma("unroll") for (int _i = 0; _i < 2; ++_i) \
;         __builtin_amdgcn_global_load_lds((const unsigned*)((const char*)(gbase) + (voff)[_i]), (PG8_LAS unsigned*)(lds + (bufoff) + ldsw + _i * 8192), 16, 0, 0); } while (0)
; #define PG8_LDA(dst, b, h) do { _Pragma("unroll") for (int m = 0; m < 4; ++m) _Pragma("unroll") for (int k = 0; k < 2; ++k) dst[m][k] = *(const PG8_LAS bf16x8*)(lds + PG8_SA(b, h) + aoff + m * 2048 + k * 1024); } while (0)
; #define PG8_LDB(dst, b, h) do { _Pragma("unroll") for (int n = 0; n < 2; ++n) _Pragma("unroll") for (int k = 0; k < 2; ++k) dst[n][k] = *(const PG8_LAS bf16x8*)(lds + PG8_SB(b, h) + boff + n * 2048 + k * 1024); } while (0)
; #define PG8_MMA(ai, bj, At, Bt) do { __builtin_amdgcn_s_setprio(1); _Pragma("unroll") for (int m = 0; m < 4; ++m) _Pragma("unroll") for (int n = 0; n < 2; ++n) _Pragma("unroll") for (int k = 0; k < 2; ++k) \
;         acc[ai][bj][m][n] = __builtin_amdgcn_mfma_f32_16x16x32_bf16(Bt[n][k], At[m][k], acc[ai][bj][m][n], 0, 0, 0); __builtin_amdgcn_s_setprio(0); } while (0)
; #define PG8_WAIT_V(n) asm volatile("s_waitcnt vmcnt(" #n ")" ::: "memory")
; #define PG8_WAIT_L(n) asm volatile("s_waitcnt lgkmcnt(" #n ")" ::: "memory")
; #define PG8_BAR __builtin_amdgcn_s_barrier()
; #define PG8_SCHED __builtin_amdgcn_sched_barrier(0)
; template <class Epi, class Sched, bool ALIGN_EPI = false, bool SP2 = false>
; __device__ __forceinline__ void gemm_phase(PG8_LAS unsigned char* lds, const Gemm g, const Sched& S, const Epi& E) {
;     ...
;             PG8_WAIT_V(8); PG8_WAIT_L(0); PG8_BAR; PG8_MMA(1, 0, At, B0); PG8_MMA(1, 1, At, B1); PG8_BAR; PG8_SCHED;
;             PG8_LDB(B0, 1, 0); PG8_LDB(B1, 1, 1); PG8_SCHED; PG8_LDA(At, 1, 0); PG8_STAGE(PG8_SA(0, 1), a2 + hstep, voffA);
;             PG8_WAIT_V(8); PG8_WAIT_L(0); PG8_BAR; PG8_MMA(0, 0, At, B0); PG8_MMA(0, 1, At, B1); PG8_BAR; PG8_SCHED;
	s_setprio 1
	s_waitcnt lgkmcnt(0)
	v_mfma_f32_16x16x32_bf16 v[50:53], v[146:149], v[178:181], v[50:53]
	v_mfma_f32_16x16x32_bf16 v[50:53], v[150:153], v[182:185], v[50:53]
	v_mfma_f32_16x16x32_bf16 v[34:37], v[146:149], v[186:189], v[34:37]
	v_mfma_f32_16x16x32_bf16 v[34:37], v[150:153], v[190:193], v[34:37]
	v_mfma_f32_16x16x32_bf16 v[18:21], v[146:149], v[202:205], v[18:21]
	v_mfma_f32_16x16x32_bf16 v[18:21], v[150:153], v[206:209], v[18:21]
	v_mfma_f32_16x16x32_bf16 v[2:5], v[146:149], v[210:213], v[2:5]
	v_mfma_f32_16x16x32_bf16 v[2:5], v[150:153], v[214:217], v[2:5]
	v_mfma_f32_16x16x32_bf16 v[54:57], v[154:157], v[178:181], v[54:57]
	v_mfma_f32_16x16x32_bf16 v[54:57], v[158:161], v[182:185], v[54:57]
	v_mfma_f32_16x16x32_bf16 v[38:41], v[154:157], v[186:189], v[38:41]
	v_mfma_f32_16x16x32_bf16 v[38:41], v[158:161], v[190:193], v[38:41]
	v_mfma_f32_16x16x32_bf16 v[22:25], v[154:157], v[202:205], v[22:25]
	v_mfma_f32_16x16x32_bf16 v[22:25], v[158:161], v[206:209], v[22:25]
	v_mfma_f32_16x16x32_bf16 v[6:9], v[154:157], v[210:213], v[6:9]
	v_mfma_f32_16x16x32_bf16 v[6:9], v[158:161], v[214:217], v[6:9]
	s_setprio 0
	s_setprio 1
	v_mfma_f32_16x16x32_bf16 v[58:61], v[162:165], v[178:181], v[58:61]
	v_mfma_f32_16x16x32_bf16 v[58:61], v[166:169], v[182:185], v[58:61]
	v_mfma_f32_16x16x32_bf16 v[42:45], v[162:165], v[186:189], v[42:45]
	v_mfma_f32_16x16x32_bf16 v[42:45], v[166:169], v[190:193], v[42:45]
	v_mfma_f32_16x16x32_bf16 v[26:29], v[162:165], v[202:205], v[26:29]
	v_mfma_f32_16x16x32_bf16 v[26:29], v[166:169], v[206:209], v[26:29]
	v_mfma_f32_16x16x32_bf16 v[10:13], v[162:165], v[210:213], v[10:13]
	v_mfma_f32_16x16x32_bf16 v[10:13], v[166:169], v[214:217], v[10:13]
	v_mfma_f32_16x16x32_bf16 v[62:65], v[170:173], v[178:181], v[62:65]
	v_mfma_f32_16x16x32_bf16 v[62:65], v[174:177], v[182:185], v[62:65]
	v_mfma_f32_16x16x32_bf16 v[46:49], v[170:173], v[186:189], v[46:49]
	v_mfma_f32_16x16x32_bf16 v[46:49], v[174:177], v[190:193], v[46:49]
	v_mfma_f32_16x16x32_bf16 v[30:33], v[170:173], v[202:205], v[30:33]
	v_mfma_f32_16x16x32_bf16 v[30:33], v[174:177], v[206:209], v[30:33]
	v_mfma_f32_16x16x32_bf16 v[14:17], v[170:173], v[210:213], v[14:17]
	v_mfma_f32_16x16x32_bf16 v[14:17], v[174:177], v[214:217], v[14:17]
	s_setprio 0
	s_barrier
	s_add_i32 s18, 0, 0x18000
	v_add_u32_e32 v145, s18, v141
	s_add_i32 s83, 0, 0x1c000
	ds_read_b128 v[146:149], v145
	ds_read_b128 v[150:153], v145 offset:1024
	ds_read_b128 v[154:157], v145 offset:2048
	ds_read_b128 v[158:161], v145 offset:3072
	v_add_u32_e32 v145, s83, v141
	ds_read_b128 v[162:165], v145
	ds_read_b128 v[166:169], v145 offset:1024
	ds_read_b128 v[170:173], v145 offset:2048
	ds_read_b128 v[174:177], v145 offset:3072
	s_add_u32 s38, s64, 0x40000
	s_addc_u32 s39, s65, 0
	s_mov_b32 m0, s58
	v_lshl_add_u64 v[224:225], s[38:39], 0, v[134:135]
	ds_read_b128 v[178:181], v144 offset:32768
	ds_read_b128 v[182:185], v144 offset:33792
	ds_read_b128 v[186:189], v144 offset:34816
	ds_read_b128 v[190:193], v144 offset:35840
	ds_read_b128 v[202:205], v144 offset:36864
	ds_read_b128 v[206:209], v144 offset:37888
	ds_read_b128 v[210:213], v144 offset:38912
	ds_read_b128 v[214:217], v144 offset:39936
	global_load_lds_dwordx4 v[224:225], off
	v_lshl_add_u64 v[224:225], s[38:39], 0, v[132:133]
	s_mov_b32 m0, s69
	s_nop 0
	global_load_lds_dwordx4 v[224:225], off
	s_waitcnt vmcnt(8)
	s_waitcnt lgkmcnt(0)
	s_barrier
	s_setprio 1
	s_waitcnt lgkmcnt(0)
	v_mfma_f32_16x16x32_bf16 v[114:117], v[146:149], v[178:181], v[114:117]
	v_mfma_f32_16x16x32_bf16 v[114:117], v[150:153], v[182:185], v[114:117]
	v_mfma_f32_16x16x32_bf16 v[98:101], v[146:149], v[186:189], v[98:101]
	v_mfma_f32_16x16x32_bf16 v[98:101], v[150:153], v[190:193], v[98:101]
	v_mfma_f32_16x16x32_bf16 v[82:85], v[146:149], v[202:205], v[82:85]
	v_mfma_f32_16x16x32_bf16 v[82:85], v[150:153], v[206:209], v[82:85]
	v_mfma_f32_16x16x32_bf16 v[66:69], v[146:149], v[210:213], v[66:69]
	v_mfma_f32_16x16x32_bf16 v[66:69], v[150:153], v[214:217], v[66:69]
	v_mfma_f32_16x16x32_bf16 v[118:121], v[154:157], v[178:181], v[118:121]
	v_mfma_f32_16x16x32_bf16 v[118:121], v[158:161], v[182:185], v[118:121]
	v_mfma_f32_16x16x32_bf16 v[102:105], v[154:157], v[186:189], v[102:105]
	v_mfma_f32_16x16x32_bf16 v[102:105], v[158:161], v[190:193], v[102:105]
	v_mfma_f32_16x16x32_bf16 v[86:89], v[154:157], v[202:205], v[86:89]
	v_mfma_f32_16x16x32_bf16 v[86:89], v[158:161], v[206:209], v[86:89]
	v_mfma_f32_16x16x32_bf16 v[70:73], v[154:157], v[210:213], v[70:73]
	v_mfma_f32_16x16x32_bf16 v[70:73], v[158:161], v[214:217], v[70:73]
	s_setprio 0
	s_setprio 1
	v_mfma_f32_16x16x32_bf16 v[122:125], v[162:165], v[178:181], v[122:125]
	v_mfma_f32_16x16x32_bf16 v[122:125], v[166:169], v[182:185], v[122:125]
	v_mfma_f32_16x16x32_bf16 v[106:109], v[162:165], v[186:189], v[106:109]
	v_mfma_f32_16x16x32_bf16 v[106:109], v[166:169], v[190:193], v[106:109]
	v_mfma_f32_16x16x32_bf16 v[90:93], v[162:165], v[202:205], v[90:93]
	v_mfma_f32_16x16x32_bf16 v[90:93], v[166:169], v[206:209], v[90:93]
	v_mfma_f32_16x16x32_bf16 v[74:77], v[162:165], v[210:213], v[74:77]
	v_mfma_f32_16x16x32_bf16 v[74:77], v[166:169], v[214:217], v[74:77]
	v_mfma_f32_16x16x32_bf16 v[126:129], v[170:173], v[178:181], v[126:129]
	v_mfma_f32_16x16x32_bf16 v[126:129], v[174:177], v[182:185], v[126:129]
	v_mfma_f32_16x16x32_bf16 v[110:113], v[170:173], v[186:189], v[110:113]
	v_mfma_f32_16x16x32_bf16 v[110:113], v[174:177], v[190:193], v[110:113]
	v_mfma_f32_16x16x32_bf16 v[94:97], v[170:173], v[202:205], v[94:97]
	v_mfma_f32_16x16x32_bf16 v[94:97], v[174:177], v[206:209], v[94:97]
	v_mfma_f32_16x16x32_bf16 v[78:81], v[170:173], v[210:213], v[78:81]
	v_mfma_f32_16x16x32_bf16 v[78:81], v[174:177], v[214:217], v[78:81]
	s_setprio 0
	s_barrier
; #define PG8_STAGE(bufoff, gbase, voff) do { _Pragma("unroll") for (int _i = 0; _i < 2; ++_i) \
;         __builtin_amdgcn_global_load_lds((const unsigned*)((const char*)(gbase) + (voff)[_i]), (PG8_LAS unsigned*)(lds + (bufoff) + ldsw + _i * 8192), 16, 0, 0); } while (0)
; #define PG8_LDA(dst, b, h) do { _Pragma("unroll") for (int m = 0; m < 4; ++m) _Pragma("unroll") for (int k = 0; k < 2; ++k) dst[m][k] = *(const PG8_LAS bf16x8*)(lds + PG8_SA(b, h) + aoff + m * 2048 + k * 1024); } while (0)
; #define PG8_LDB(dst, b, h) do { _Pragma("unroll") for (int n = 0; n < 2; ++n) _Pragma("unroll") for (int k = 0; k < 2; ++k) dst[n][k] = *(const PG8_LAS bf16x8*)(lds + PG8_SB(b, h) + boff + n * 2048 + k * 1024); } while (0)
; template <class Epi, class Sched, bool ALIGN_EPI = false, bool SP2 = false>
; __device__ __forceinline__ void gemm_phase(PG8_LAS unsigned char* lds, const Gemm g, const Sched& S, const Epi& E) {
;     ...
;         for (int t = 0; t < nt; t += 2) {
;             const bool last = (t == nt - 2);
;             const char* a1 = cA + (size_t)(t + 1) * kstep;
;             const char* a2 = last ? nA : cA + (size_t)(t + 2) * kstep; const char* b2 = last ? nB : cB + (size_t)(t + 2) * kstep;
;             const char* a3 = a2 + kstep; const char* b3 = b2 + kstep;
;             if (last && has_next) S.a_ready(nxt);
;             if constexpr (SP2) {
;             PG8_LDB(B0, 0, 0); PG8_LDB(B1, 0, 1); PG8_SCHED; PG8_LDA(At, 0, 0); PG8_STAGE(PG8_SA(1, 1), a1 + hstep, voffA);
;             PG8_WAIT_V(8); PG8_WAIT_L(0); PG8_BAR; PG8_MMA(0, 0, At, B0); PG8_MMA(0, 1, At, B1); PG8_BAR; PG8_SCHED;
;             PG8_LDA(At, 0, 1); PG8_STAGE(PG8_SB(0, 0), b2, voffB); PG8_STAGE(PG8_SB(0, 1), b2 + hstep, voffB); PG8_STAGE(PG8_SA(0, 0), a2, voffA);
;             PG8_WAIT_V(8); PG8_WAIT_L(0); PG8_BAR; PG8_MMA(1, 0, At, B0); PG8_MMA(1, 1, At, B1); PG8_BAR; PG8_SCHED;
;             PG8_LDB(B0, 1, 0); PG8_LDB(B1, 1, 1); PG8_SCHED; PG8_LDA(At, 1, 0); PG8_STAGE(PG8_SA(0, 1), a2 + hstep, voffA);
;             PG8_WAIT_V(8); PG8_WAIT_L(0); PG8_BAR; PG8_MMA(0, 0, At, B0); PG8_MMA(0, 1, At, B1); PG8_BAR; PG8_SCHED;
;             PG8_LDA(At, 1, 1); PG8_STAGE(PG8_SB(1, 0), b3, voffB); PG8_STAGE(PG8_SB(1, 1), b3 + hstep, voffB); PG8_STAGE(PG8_SA(1, 0), a3, voffA);
;             PG8_WAIT_V(8); PG8_WAIT_L(0); PG8_BAR; PG8_MMA(1, 0, At, B0); PG8_MMA(1, 1, At, B1); PG8_BAR; PG8_SCHED;
	s_add_i32 s18, s18, s27
	v_lshl_add_u64 v[194:195], v[194:195], 0, s[30:31]
	s_mov_b32 m0, s18
	ds_read_b128 v[178:181], v144 offset:49152
	ds_read_b128 v[182:185], v144 offset:50176
	ds_read_b128 v[186:189], v144 offset:51200
	ds_read_b128 v[190:193], v144 offset:52224
	ds_read_b128 v[202:205], v144 offset:53248
	ds_read_b128 v[206:209], v144 offset:54272
	ds_read_b128 v[210:213], v144 offset:55296
	ds_read_b128 v[214:217], v144 offset:56320
	global_load_lds_dwordx4 v[194:195], off
	s_add_i32 m0, s18, 0x2000
	s_add_u32 s38, s56, 0x40080
	v_lshl_add_u64 v[194:195], v[218:219], 0, s[30:31]
	s_addc_u32 s39, s57, 0
	s_add_i32 s18, s83, s27
	global_load_lds_dwordx4 v[194:195], off
	v_lshl_add_u64 v[194:195], s[38:39], 0, v[0:1]
	s_mov_b32 m0, s18
	s_nop 0
	global_load_lds_dwordx4 v[194:195], off
	v_lshl_add_u64 v[194:195], s[38:39], 0, v[130:131]
	s_add_i32 m0, s18, 0x2000
	s_nop 0
	global_load_lds_dwordx4 v[194:195], off
	v_lshl_add_u64 v[194:195], v[220:221], 0, s[30:31]
	s_mov_b32 m0, s71
	s_nop 0
	global_load_lds_dwordx4 v[194:195], off
	v_lshl_add_u64 v[194:195], v[222:223], 0, s[30:31]
	s_mov_b32 m0, s72
	s_nop 0
	global_load_lds_dwordx4 v[194:195], off
	s_waitcnt vmcnt(8)
	s_waitcnt lgkmcnt(0)
	s_barrier
	s_setprio 1
	s_waitcnt lgkmcnt(0)
	v_mfma_f32_16x16x32_bf16 v[50:53], v[146:149], v[178:181], v[50:53]
	v_mfma_f32_16x16x32_bf16 v[50:53], v[150:153], v[182:185], v[50:53]
	v_mfma_f32_16x16x32_bf16 v[34:37], v[146:149], v[186:189], v[34:37]
	v_mfma_f32_16x16x32_bf16 v[34:37], v[150:153], v[190:193], v[34:37]
	v_mfma_f32_16x16x32_bf16 v[18:21], v[146:149], v[202:205], v[18:21]
	v_mfma_f32_16x16x32_bf16 v[18:21], v[150:153], v[206:209], v[18:21]
	v_mfma_f32_16x16x32_bf16 v[2:5], v[146:149], v[210:213], v[2:5]
	v_mfma_f32_16x16x32_bf16 v[2:5], v[150:153], v[214:217], v[2:5]
	v_mfma_f32_16x16x32_bf16 v[54:57], v[154:157], v[178:181], v[54:57]
	v_mfma_f32_16x16x32_bf16 v[54:57], v[158:161], v[182:185], v[54:57]
	v_mfma_f32_16x16x32_bf16 v[38:41], v[154:157], v[186:189], v[38:41]
	v_mfma_f32_16x16x32_bf16 v[38:41], v[158:161], v[190:193], v[38:41]
	v_mfma_f32_16x16x32_bf16 v[22:25], v[154:157], v[202:205], v[22:25]
	v_mfma_f32_16x16x32_bf16 v[22:25], v[158:161], v[206:209], v[22:25]
	v_mfma_f32_16x16x32_bf16 v[6:9], v[154:157], v[210:213], v[6:9]
	v_mfma_f32_16x16x32_bf16 v[6:9], v[158:161], v[214:217], v[6:9]
	s_setprio 0
	s_setprio 1
	v_mfma_f32_16x16x32_bf16 v[58:61], v[162:165], v[178:181], v[58:61]
	v_mfma_f32_16x16x32_bf16 v[58:61], v[166:169], v[182:185], v[58:61]
	v_mfma_f32_16x16x32_bf16 v[42:45], v[162:165], v[186:189], v[42:45]
	v_mfma_f32_16x16x32_bf16 v[42:45], v[166:169], v[190:193], v[42:45]
	v_mfma_f32_16x16x32_bf16 v[26:29], v[162:165], v[202:205], v[26:29]
	v_mfma_f32_16x16x32_bf16 v[26:29], v[166:169], v[206:209], v[26:29]
	v_mfma_f32_16x16x32_bf16 v[10:13], v[162:165], v[210:213], v[10:13]
	v_mfma_f32_16x16x32_bf16 v[10:13], v[166:169], v[214:217], v[10:13]
	v_mfma_f32_16x16x32_bf16 v[62:65], v[170:173], v[178:181], v[62:65]
	v_mfma_f32_16x16x32_bf16 v[62:65], v[174:177], v[182:185], v[62:65]
	v_mfma_f32_16x16x32_bf16 v[46:49], v[170:173], v[186:189], v[46:49]
	v_mfma_f32_16x16x32_bf16 v[46:49], v[174:177], v[190:193], v[46:49]
	v_mfma_f32_16x16x32_bf16 v[30:33], v[170:173], v[202:205], v[30:33]
	v_mfma_f32_16x16x32_bf16 v[30:33], v[174:177], v[206:209], v[30:33]
	v_mfma_f32_16x16x32_bf16 v[14:17], v[170:173], v[210:213], v[14:17]
	v_mfma_f32_16x16x32_bf16 v[14:17], v[174:177], v[214:217], v[14:17]
	s_setprio 0
	s_barrier
	s_add_i32 s82, s82, 2
	s_add_u32 s60, s60, 0x100
	s_addc_u32 s61, s61, 0
	s_add_u32 s80, s80, 0x100
	s_addc_u32 s81, s81, 0
	s_cmp_gt_u32 s82, 13
	s_cbranch_scc0 .LBB0_220
	s_and_b64 vcc, exec, s[44:45]
	s_cbranch_vccz .LBB0_223
	s_barrier

; #define PG8_STAGE(bufoff, gbase, voff) do { _Pragma("unroll") for (int _i = 0; _i < 2; ++_i) \
;         __builtin_amdgcn_global_load_lds((const unsigned*)((const char*)(gbase) + (voff)[_i]), (PG8_LAS unsigned*)(lds + (bufoff) + ldsw + _i * 8192), 16, 0, 0); } while (0)
; #define PG8_LDA(dst, b, h) do { _Pragma("unroll") for (int m = 0; m < 4; ++m) _Pragma("unroll") for (int k = 0; k < 2; ++k) dst[m][k] = *(const PG8_LAS bf16x8*)(lds + PG8_SA(b, h) + aoff + m * 2048 + k * 1024); } while (0)
; #define PG8_LDB(dst, b, h) do { _Pragma("unroll") for (int n = 0; n < 2; ++n) _Pragma("unroll") for (int k = 0; k < 2; ++k) dst[n][k] = *(const PG8_LAS bf16x8*)(lds + PG8_SB(b, h) + boff + n * 2048 + k * 1024); } while (0)
; #define PG8_MMA(ai, bj, At, Bt) do { __builtin_amdgcn_s_setprio(1); _Pragma("unroll") for (int m = 0; m < 4; ++m) _Pragma("unroll") for (int n = 0; n < 2; ++n) _Pragma("unroll") for (int k = 0; k < 2; ++k) \
;         acc[ai][bj][m][n] = __builtin_amdgcn_mfma_f32_16x16x32_bf16(Bt[n][k], At[m][k], acc[ai][bj][m][n], 0, 0, 0); __builtin_amdgcn_s_setprio(0); } while (0)
; #define PG8_WAIT_V(n) asm volatile("s_waitcnt vmcnt(" #n ")" ::: "memory")
; #define PG8_WAIT_L(n) asm volatile("s_waitcnt lgkmcnt(" #n ")" ::: "memory")
; #define PG8_BAR __builtin_amdgcn_s_barrier()
; #define PG8_SCHED __builtin_amdgcn_sched_barrier(0)
; template <class Epi, class Sched, bool ALIGN_EPI = false, bool SP2 = false>
; __device__ __forceinline__ void gemm_phase(PG8_LAS unsigned char* lds, const Gemm g, const Sched& S, const Epi& E) {
;     ...
;         for (int t = 0; t < nt; t += 2) {
;             const bool last = (t == nt - 2);
;             const char* a1 = cA + (size_t)(t + 1) * kstep;
;             const char* a2 = last ? nA : cA + (size_t)(t + 2) * kstep; const char* b2 = last ? nB : cB + (size_t)(t + 2) * kstep;
;             const char* a3 = a2 + kstep; const char* b3 = b2 + kstep;
;             if (last && has_next) S.a_ready(nxt);
;             if constexpr (SP2) {
;             PG8_LDB(B0, 0, 0); PG8_LDB(B1, 0, 1); PG8_SCHED; PG8_LDA(At, 0, 0); PG8_STAGE(PG8_SA(1, 1), a1 + hstep, voffA);
;             PG8_WAIT_V(8); PG8_WAIT_L(0); PG8_BAR; PG8_MMA(0, 0, At, B0); PG8_MMA(0, 1, At, B1); PG8_BAR; PG8_SCHED;
;             PG8_LDA(At, 0, 1); PG8_STAGE(PG8_SB(0, 0), b2, voffB); PG8_STAGE(PG8_SB(0, 1), b2 + hstep, voffB); PG8_STAGE(PG8_SA(0, 0), a2, voffA);
.LBB0_274:
	s_add_i32 vcc_lo, s46, 2
	s_add_u32 s38, s48, 0x80
	s_addc_u32 s39, s49, 0
	s_add_i32 vcc_hi, 0, 0x10000
	s_cmp_eq_u32 s99, s46
	s_cselect_b32 s47, s81, s39
	s_cselect_b32 s46, s80, s38
	s_cselect_b32 s39, s83, s51
	s_cselect_b32 s38, s82, s50
	s_add_i32 s18, 0, 0x14000
	v_add_u32_e32 v142, vcc_hi, v245
	v_add_u32_e32 v158, s18, v245
	ds_read_b128 v[110:113], v142
	ds_read_b128 v[118:121], v142 offset:1024
	ds_read_b128 v[138:141], v142 offset:2048
	ds_read_b128 v[142:145], v142 offset:3072
	ds_read_b128 v[146:149], v158
	ds_read_b128 v[150:153], v158 offset:1024
	ds_read_b128 v[154:157], v158 offset:2048
	ds_read_b128 v[158:161], v158 offset:3072
	v_lshl_add_u64 v[210:211], s[48:49], 0, v[206:207]
	s_add_i32 m0, s92, 0xc000
	ds_read_b128 v[162:165], v247
	ds_read_b128 v[166:169], v247 offset:1024
	ds_read_b128 v[170:173], v247 offset:2048
	ds_read_b128 v[174:177], v247 offset:3072
	ds_read_b128 v[178:181], v247 offset:4096
	ds_read_b128 v[182:185], v247 offset:5120
	ds_read_b128 v[186:189], v247 offset:6144
	ds_read_b128 v[190:193], v247 offset:7168
	global_load_lds_dwordx4 v[210:211], off
	v_lshl_add_u64 v[210:211], s[48:49], 0, v[208:209]
	s_add_i32 m0, s92, 0xe000
	s_nop 0
	global_load_lds_dwordx4 v[210:211], off
	s_waitcnt vmcnt(8)
	s_waitcnt lgkmcnt(0)
	s_barrier
	s_setprio 1
	s_waitcnt lgkmcnt(0)
	v_mfma_f32_16x16x32_bf16 v[130:133], v[110:113], v[162:165], v[130:133]
	v_mfma_f32_16x16x32_bf16 v[130:133], v[118:121], v[166:169], v[130:133]
	v_mfma_f32_16x16x32_bf16 v[114:117], v[110:113], v[170:173], v[114:117]
	v_mfma_f32_16x16x32_bf16 v[114:117], v[118:121], v[174:177], v[114:117]
	v_mfma_f32_16x16x32_bf16 v[94:97], v[110:113], v[178:181], v[94:97]
	v_mfma_f32_16x16x32_bf16 v[94:97], v[118:121], v[182:185], v[94:97]
	v_mfma_f32_16x16x32_bf16 v[78:81], v[110:113], v[186:189], v[78:81]
	v_mfma_f32_16x16x32_bf16 v[78:81], v[118:121], v[190:193], v[78:81]
	v_mfma_f32_16x16x32_bf16 v[134:137], v[138:141], v[162:165], v[134:137]
	v_mfma_f32_16x16x32_bf16 v[134:137], v[142:145], v[166:169], v[134:137]
	v_mfma_f32_16x16x32_bf16 v[106:109], v[138:141], v[170:173], v[106:109]
	v_mfma_f32_16x16x32_bf16 v[106:109], v[142:145], v[174:177], v[106:109]
	v_mfma_f32_16x16x32_bf16 v[90:93], v[138:141], v[178:181], v[90:93]
	v_mfma_f32_16x16x32_bf16 v[90:93], v[142:145], v[182:185], v[90:93]
	v_mfma_f32_16x16x32_bf16 v[74:77], v[138:141], v[186:189], v[74:77]
	v_mfma_f32_16x16x32_bf16 v[74:77], v[142:145], v[190:193], v[74:77]
	s_setprio 0
	s_setprio 1
	v_mfma_f32_16x16x32_bf16 v[126:129], v[146:149], v[162:165], v[126:129]
	v_mfma_f32_16x16x32_bf16 v[126:129], v[150:153], v[166:169], v[126:129]
	v_mfma_f32_16x16x32_bf16 v[102:105], v[146:149], v[170:173], v[102:105]
	v_mfma_f32_16x16x32_bf16 v[102:105], v[150:153], v[174:177], v[102:105]
	v_mfma_f32_16x16x32_bf16 v[86:89], v[146:149], v[178:181], v[86:89]
	v_mfma_f32_16x16x32_bf16 v[86:89], v[150:153], v[182:185], v[86:89]
	v_mfma_f32_16x16x32_bf16 v[70:73], v[146:149], v[186:189], v[70:73]
	v_mfma_f32_16x16x32_bf16 v[70:73], v[150:153], v[190:193], v[70:73]
	v_mfma_f32_16x16x32_bf16 v[122:125], v[154:157], v[162:165], v[122:125]
	v_mfma_f32_16x16x32_bf16 v[122:125], v[158:161], v[166:169], v[122:125]
	v_mfma_f32_16x16x32_bf16 v[98:101], v[154:157], v[170:173], v[98:101]
	v_mfma_f32_16x16x32_bf16 v[98:101], v[158:161], v[174:177], v[98:101]
	v_mfma_f32_16x16x32_bf16 v[82:85], v[154:157], v[178:181], v[82:85]
	v_mfma_f32_16x16x32_bf16 v[82:85], v[158:161], v[182:185], v[82:85]
	v_mfma_f32_16x16x32_bf16 v[66:69], v[154:157], v[186:189], v[66:69]
	v_mfma_f32_16x16x32_bf16 v[66:69], v[158:161], v[190:193], v[66:69]
	s_setprio 0
	s_barrier
	s_add_i32 vcc_hi, vcc_hi, s6
	v_lshl_add_u64 v[210:211], s[38:39], 0, v[0:1]
	s_mov_b32 m0, vcc_hi
	ds_read_b128 v[162:165], v247 offset:16384
	ds_read_b128 v[166:169], v247 offset:17408
	ds_read_b128 v[170:173], v247 offset:18432
	ds_read_b128 v[174:177], v247 offset:19456
	ds_read_b128 v[178:181], v247 offset:20480
	ds_read_b128 v[182:185], v247 offset:21504
	ds_read_b128 v[186:189], v247 offset:22528
	ds_read_b128 v[190:193], v247 offset:23552
	global_load_lds_dwordx4 v[210:211], off
	s_add_i32 m0, vcc_hi, 0x2000
	v_lshl_add_u64 v[212:213], s[38:39], 0, v[204:205]
	s_add_u32 s38, s38, s58
	s_addc_u32 s39, s39, 0
	s_add_i32 s18, s18, s6
	global_load_lds_dwordx4 v[212:213], off
	v_lshl_add_u64 v[214:215], s[38:39], 0, v[0:1]
	s_mov_b32 m0, s18
	v_lshl_add_u64 v[216:217], s[38:39], 0, v[204:205]
	global_load_lds_dwordx4 v[214:215], off
	s_add_i32 m0, s18, 0x2000
	v_lshl_add_u64 v[218:219], s[46:47], 0, v[194:195]
	global_load_lds_dwordx4 v[216:217], off
	s_mov_b32 m0, s92
	v_lshl_add_u64 v[220:221], s[46:47], 0, v[202:203]
	global_load_lds_dwordx4 v[218:219], off
	s_mov_b32 m0, s93
	s_nop 0
	global_load_lds_dwordx4 v[220:221], off
	s_waitcnt vmcnt(8)
	s_waitcnt lgkmcnt(0)
	s_barrier
; #define PG8_STAGE(bufoff, gbase, voff) do { _Pragma("unroll") for (int _i = 0; _i < 2; ++_i) \
;         __builtin_amdgcn_global_load_lds((const unsigned*)((const char*)(gbase) + (voff)[_i]), (PG8_LAS unsigned*)(lds + (bufoff) + ldsw + _i * 8192), 16, 0, 0); } while (0)
; #define PG8_LDA(dst, b, h) do { _Pragma("unroll") for (int m = 0; m < 4; ++m) _Pragma("unroll") for (int k = 0; k < 2; ++k) dst[m][k] = *(const PG8_LAS bf16x8*)(lds + PG8_SA(b, h) + aoff + m * 2048 + k * 1024); } while (0)
; #define PG8_LDB(dst, b, h) do { _Pragma("unroll") for (int n = 0; n < 2; ++n) _Pragma("unroll") for (int k = 0; k < 2; ++k) dst[n][k] = *(const PG8_LAS bf16x8*)(lds + PG8_SB(b, h) + boff + n * 2048 + k * 1024); } while (0)
; #define PG8_MMA(ai, bj, At, Bt) do { __builtin_amdgcn_s_setprio(1); _Pragma("unroll") for (int m = 0; m < 4; ++m) _Pragma("unroll") for (int n = 0; n < 2; ++n) _Pragma("unroll") for (int k = 0; k < 2; ++k) \
;         acc[ai][bj][m][n] = __builtin_amdgcn_mfma_f32_16x16x32_bf16(Bt[n][k], At[m][k], acc[ai][bj][m][n], 0, 0, 0); __builtin_amdgcn_s_setprio(0); } while (0)
; #define PG8_WAIT_V(n) asm volatile("s_waitcnt vmcnt(" #n ")" ::: "memory")
; #define PG8_WAIT_L(n) asm volatile("s_waitcnt lgkmcnt(" #n ")" ::: "memory")
; #define PG8_BAR __builtin_amdgcn_s_barrier()
; #define PG8_SCHED __builtin_amdgcn_sched_barrier(0)
; template <class Epi, class Sched, bool ALIGN_EPI = false, bool SP2 = false>
; __device__ __forceinline__ void gemm_phase(PG8_LAS unsigned char* lds, const Gemm g, const Sched& S, const Epi& E) {
;     ...
;             PG8_WAIT_V(8); PG8_WAIT_L(0); PG8_BAR; PG8_MMA(1, 0, At, B0); PG8_MMA(1, 1, At, B1); PG8_BAR; PG8_SCHED;
;             PG8_LDB(B0, 1, 0); PG8_LDB(B1, 1, 1); PG8_SCHED; PG8_LDA(At, 1, 0); PG8_STAGE(PG8_SA(0, 1), a2 + hstep, voffA);
;             PG8_WAIT_V(8); PG8_WAIT_L(0); PG8_BAR; PG8_MMA(0, 0, At, B0); PG8_MMA(0, 1, At, B1); PG8_BAR; PG8_SCHED;
	s_setprio 1
	s_waitcnt lgkmcnt(0)
	v_mfma_f32_16x16x32_bf16 v[62:65], v[110:113], v[162:165], v[62:65]
	v_mfma_f32_16x16x32_bf16 v[62:65], v[118:121], v[166:169], v[62:65]
	v_mfma_f32_16x16x32_bf16 v[46:49], v[110:113], v[170:173], v[46:49]
	v_mfma_f32_16x16x32_bf16 v[46:49], v[118:121], v[174:177], v[46:49]
	v_mfma_f32_16x16x32_bf16 v[30:33], v[110:113], v[178:181], v[30:33]
	v_mfma_f32_16x16x32_bf16 v[30:33], v[118:121], v[182:185], v[30:33]
	v_mfma_f32_16x16x32_bf16 v[14:17], v[110:113], v[186:189], v[14:17]
	v_mfma_f32_16x16x32_bf16 v[14:17], v[118:121], v[190:193], v[14:17]
	v_mfma_f32_16x16x32_bf16 v[58:61], v[138:141], v[162:165], v[58:61]
	v_mfma_f32_16x16x32_bf16 v[58:61], v[142:145], v[166:169], v[58:61]
	v_mfma_f32_16x16x32_bf16 v[42:45], v[138:141], v[170:173], v[42:45]
	v_mfma_f32_16x16x32_bf16 v[42:45], v[142:145], v[174:177], v[42:45]
	v_mfma_f32_16x16x32_bf16 v[26:29], v[138:141], v[178:181], v[26:29]
	v_mfma_f32_16x16x32_bf16 v[26:29], v[142:145], v[182:185], v[26:29]
	v_mfma_f32_16x16x32_bf16 v[10:13], v[138:141], v[186:189], v[10:13]
	v_mfma_f32_16x16x32_bf16 v[10:13], v[142:145], v[190:193], v[10:13]
	s_setprio 0
	s_setprio 1
	v_mfma_f32_16x16x32_bf16 v[54:57], v[146:149], v[162:165], v[54:57]
	v_mfma_f32_16x16x32_bf16 v[54:57], v[150:153], v[166:169], v[54:57]
	v_mfma_f32_16x16x32_bf16 v[38:41], v[146:149], v[170:173], v[38:41]
	v_mfma_f32_16x16x32_bf16 v[38:41], v[150:153], v[174:177], v[38:41]
	v_mfma_f32_16x16x32_bf16 v[22:25], v[146:149], v[178:181], v[22:25]
	v_mfma_f32_16x16x32_bf16 v[22:25], v[150:153], v[182:185], v[22:25]
	v_mfma_f32_16x16x32_bf16 v[6:9], v[146:149], v[186:189], v[6:9]
	v_mfma_f32_16x16x32_bf16 v[6:9], v[150:153], v[190:193], v[6:9]
	v_mfma_f32_16x16x32_bf16 v[50:53], v[154:157], v[162:165], v[50:53]
	v_mfma_f32_16x16x32_bf16 v[50:53], v[158:161], v[166:169], v[50:53]
	v_mfma_f32_16x16x32_bf16 v[34:37], v[154:157], v[170:173], v[34:37]
	v_mfma_f32_16x16x32_bf16 v[34:37], v[158:161], v[174:177], v[34:37]
	v_mfma_f32_16x16x32_bf16 v[18:21], v[154:157], v[178:181], v[18:21]
	v_mfma_f32_16x16x32_bf16 v[18:21], v[158:161], v[182:185], v[18:21]
	v_mfma_f32_16x16x32_bf16 v[2:5], v[154:157], v[186:189], v[2:5]
	v_mfma_f32_16x16x32_bf16 v[2:5], v[158:161], v[190:193], v[2:5]
	s_setprio 0
	s_barrier
	s_add_i32 s18, 0, 0x18000
	s_add_i32 vcc_hi, 0, 0x1c000
	v_add_u32_e32 v142, s18, v245
	v_add_u32_e32 v158, vcc_hi, v245
	ds_read_b128 v[110:113], v142
	ds_read_b128 v[118:121], v142 offset:1024
	ds_read_b128 v[138:141], v142 offset:2048
	ds_read_b128 v[142:145], v142 offset:3072
	ds_read_b128 v[146:149], v158
	ds_read_b128 v[150:153], v158 offset:1024
	ds_read_b128 v[154:157], v158 offset:2048
	ds_read_b128 v[158:161], v158 offset:3072
	s_add_u32 s38, s46, s58
	s_addc_u32 s39, s47, 0
	s_mov_b32 m0, s94
	v_lshl_add_u64 v[222:223], s[38:39], 0, v[194:195]
	ds_read_b128 v[162:165], v247 offset:32768
	ds_read_b128 v[166:169], v247 offset:33792
	ds_read_b128 v[170:173], v247 offset:34816
	ds_read_b128 v[174:177], v247 offset:35840
	ds_read_b128 v[178:181], v247 offset:36864
	ds_read_b128 v[182:185], v247 offset:37888
	ds_read_b128 v[186:189], v247 offset:38912
	ds_read_b128 v[190:193], v247 offset:39936
	global_load_lds_dwordx4 v[222:223], off
	v_lshl_add_u64 v[222:223], s[38:39], 0, v[202:203]
	s_mov_b32 m0, s95
	s_nop 0
	global_load_lds_dwordx4 v[222:223], off
	s_waitcnt vmcnt(8)
	s_waitcnt lgkmcnt(0)
	s_barrier
	s_setprio 1
	s_waitcnt lgkmcnt(0)
	v_mfma_f32_16x16x32_bf16 v[130:133], v[110:113], v[162:165], v[130:133]
	v_mfma_f32_16x16x32_bf16 v[130:133], v[118:121], v[166:169], v[130:133]
	v_mfma_f32_16x16x32_bf16 v[114:117], v[110:113], v[170:173], v[114:117]
	v_mfma_f32_16x16x32_bf16 v[114:117], v[118:121], v[174:177], v[114:117]
	v_mfma_f32_16x16x32_bf16 v[94:97], v[110:113], v[178:181], v[94:97]
	v_mfma_f32_16x16x32_bf16 v[94:97], v[118:121], v[182:185], v[94:97]
	v_mfma_f32_16x16x32_bf16 v[78:81], v[110:113], v[186:189], v[78:81]
	v_mfma_f32_16x16x32_bf16 v[78:81], v[118:121], v[190:193], v[78:81]
	v_mfma_f32_16x16x32_bf16 v[134:137], v[138:141], v[162:165], v[134:137]
	v_mfma_f32_16x16x32_bf16 v[134:137], v[142:145], v[166:169], v[134:137]
	v_mfma_f32_16x16x32_bf16 v[106:109], v[138:141], v[170:173], v[106:109]
	v_mfma_f32_16x16x32_bf16 v[106:109], v[142:145], v[174:177], v[106:109]
	v_mfma_f32_16x16x32_bf16 v[90:93], v[138:141], v[178:181], v[90:93]
	v_mfma_f32_16x16x32_bf16 v[90:93], v[142:145], v[182:185], v[90:93]
	v_mfma_f32_16x16x32_bf16 v[74:77], v[138:141], v[186:189], v[74:77]
	v_mfma_f32_16x16x32_bf16 v[74:77], v[142:145], v[190:193], v[74:77]
	s_setprio 0
	s_setprio 1
	v_mfma_f32_16x16x32_bf16 v[126:129], v[146:149], v[162:165], v[126:129]
	v_mfma_f32_16x16x32_bf16 v[126:129], v[150:153], v[166:169], v[126:129]
	v_mfma_f32_16x16x32_bf16 v[102:105], v[146:149], v[170:173], v[102:105]
	v_mfma_f32_16x16x32_bf16 v[102:105], v[150:153], v[174:177], v[102:105]
	v_mfma_f32_16x16x32_bf16 v[86:89], v[146:149], v[178:181], v[86:89]
	v_mfma_f32_16x16x32_bf16 v[86:89], v[150:153], v[182:185], v[86:89]
	v_mfma_f32_16x16x32_bf16 v[70:73], v[146:149], v[186:189], v[70:73]
	v_mfma_f32_16x16x32_bf16 v[70:73], v[150:153], v[190:193], v[70:73]
	v_mfma_f32_16x16x32_bf16 v[122:125], v[154:157], v[162:165], v[122:125]
	v_mfma_f32_16x16x32_bf16 v[122:125], v[158:161], v[166:169], v[122:125]
	v_mfma_f32_16x16x32_bf16 v[98:101], v[154:157], v[170:173], v[98:101]
	v_mfma_f32_16x16x32_bf16 v[98:101], v[158:161], v[174:177], v[98:101]
	v_mfma_f32_16x16x32_bf16 v[82:85], v[154:157], v[178:181], v[82:85]
	v_mfma_f32_16x16x32_bf16 v[82:85], v[158:161], v[182:185], v[82:85]
	v_mfma_f32_16x16x32_bf16 v[66:69], v[154:157], v[186:189], v[66:69]
	v_mfma_f32_16x16x32_bf16 v[66:69], v[158:161], v[190:193], v[66:69]
	s_setprio 0
	s_barrier
; #define PG8_STAGE(bufoff, gbase, voff) do { _Pragma("unroll") for (int _i = 0; _i < 2; ++_i) \
;         __builtin_amdgcn_global_load_lds((const unsigned*)((const char*)(gbase) + (voff)[_i]), (PG8_LAS unsigned*)(lds + (bufoff) + ldsw + _i * 8192), 16, 0, 0); } while (0)
; #define PG8_LDA(dst, b, h) do { _Pragma("unroll") for (int m = 0; m < 4; ++m) _Pragma("unroll") for (int k = 0; k < 2; ++k) dst[m][k] = *(const PG8_LAS bf16x8*)(lds + PG8_SA(b, h) + aoff + m * 2048 + k * 1024); } while (0)
; #define PG8_LDB(dst, b, h) do { _Pragma("unroll") for (int n = 0; n < 2; ++n) _Pragma("unroll") for (int k = 0; k < 2; ++k) dst[n][k] = *(const PG8_LAS bf16x8*)(lds + PG8_SB(b, h) + boff + n * 2048 + k * 1024); } while (0)
; template <class Epi, class Sched, bool ALIGN_EPI = false, bool SP2 = false>
; __device__ __forceinline__ void gemm_phase(PG8_LAS unsigned char* lds, const Gemm g, const Sched& S, const Epi& E) {
;     ...
;         for (int t = 0; t < nt; t += 2) {
;             const bool last = (t == nt - 2);
;             const char* a1 = cA + (size_t)(t + 1) * kstep;
;             const char* a2 = last ? nA : cA + (size_t)(t + 2) * kstep; const char* b2 = last ? nB : cB + (size_t)(t + 2) * kstep;
;             const char* a3 = a2 + kstep; const char* b3 = b2 + kstep;
;             if (last && has_next) S.a_ready(nxt);
;             if constexpr (SP2) {
;             PG8_LDB(B0, 0, 0); PG8_LDB(B1, 0, 1); PG8_SCHED; PG8_LDA(At, 0, 0); PG8_STAGE(PG8_SA(1, 1), a1 + hstep, voffA);
;             PG8_WAIT_V(8); PG8_WAIT_L(0); PG8_BAR; PG8_MMA(0, 0, At, B0); PG8_MMA(0, 1, At, B1); PG8_BAR; PG8_SCHED;
;             PG8_LDA(At, 0, 1); PG8_STAGE(PG8_SB(0, 0), b2, voffB); PG8_STAGE(PG8_SB(0, 1), b2 + hstep, voffB); PG8_STAGE(PG8_SA(0, 0), a2, voffA);
;             PG8_WAIT_V(8); PG8_WAIT_L(0); PG8_BAR; PG8_MMA(1, 0, At, B0); PG8_MMA(1, 1, At, B1); PG8_BAR; PG8_SCHED;
;             PG8_LDB(B0, 1, 0); PG8_LDB(B1, 1, 1); PG8_SCHED; PG8_LDA(At, 1, 0); PG8_STAGE(PG8_SA(0, 1), a2 + hstep, voffA);
;             PG8_WAIT_V(8); PG8_WAIT_L(0); PG8_BAR; PG8_MMA(0, 0, At, B0); PG8_MMA(0, 1, At, B1); PG8_BAR; PG8_SCHED;
;             PG8_LDA(At, 1, 1); PG8_STAGE(PG8_SB(1, 0), b3, voffB); PG8_STAGE(PG8_SB(1, 1), b3 + hstep, voffB); PG8_STAGE(PG8_SA(1, 0), a3, voffA);
;             PG8_WAIT_V(8); PG8_WAIT_L(0); PG8_BAR; PG8_MMA(1, 0, At, B0); PG8_MMA(1, 1, At, B1); PG8_BAR; PG8_SCHED;
	s_add_i32 s18, s18, s6
	v_lshl_add_u64 v[210:211], v[210:211], 0, s[30:31]
	s_mov_b32 m0, s18
	ds_read_b128 v[162:165], v247 offset:49152
	ds_read_b128 v[166:169], v247 offset:50176
	ds_read_b128 v[170:173], v247 offset:51200
	ds_read_b128 v[174:177], v247 offset:52224
	ds_read_b128 v[178:181], v247 offset:53248
	ds_read_b128 v[182:185], v247 offset:54272
	ds_read_b128 v[186:189], v247 offset:55296
	ds_read_b128 v[190:193], v247 offset:56320
	global_load_lds_dwordx4 v[210:211], off
	v_lshl_add_u64 v[210:211], v[212:213], 0, s[30:31]
	s_add_i32 m0, s18, 0x2000
	s_add_i32 s18, vcc_hi, s6
	global_load_lds_dwordx4 v[210:211], off
	v_lshl_add_u64 v[210:211], v[214:215], 0, s[30:31]
	s_mov_b32 m0, s18
	s_nop 0
	global_load_lds_dwordx4 v[210:211], off
	v_lshl_add_u64 v[210:211], v[216:217], 0, s[30:31]
	s_add_i32 m0, s18, 0x2000
	s_nop 0
	global_load_lds_dwordx4 v[210:211], off
	v_lshl_add_u64 v[210:211], v[218:219], 0, s[30:31]
	s_mov_b32 m0, s97
	s_nop 0
	global_load_lds_dwordx4 v[210:211], off
	v_lshl_add_u64 v[210:211], v[220:221], 0, s[30:31]
	s_mov_b32 m0, s98
	s_nop 0
	global_load_lds_dwordx4 v[210:211], off
	s_waitcnt vmcnt(8)
	s_waitcnt lgkmcnt(0)
	s_barrier
	s_setprio 1
	s_waitcnt lgkmcnt(0)
	v_mfma_f32_16x16x32_bf16 v[62:65], v[110:113], v[162:165], v[62:65]
	v_mfma_f32_16x16x32_bf16 v[62:65], v[118:121], v[166:169], v[62:65]
	v_mfma_f32_16x16x32_bf16 v[46:49], v[110:113], v[170:173], v[46:49]
	v_mfma_f32_16x16x32_bf16 v[46:49], v[118:121], v[174:177], v[46:49]
	v_mfma_f32_16x16x32_bf16 v[30:33], v[110:113], v[178:181], v[30:33]
	v_mfma_f32_16x16x32_bf16 v[30:33], v[118:121], v[182:185], v[30:33]
	v_mfma_f32_16x16x32_bf16 v[14:17], v[110:113], v[186:189], v[14:17]
	v_mfma_f32_16x16x32_bf16 v[14:17], v[118:121], v[190:193], v[14:17]
	v_mfma_f32_16x16x32_bf16 v[58:61], v[138:141], v[162:165], v[58:61]
	v_mfma_f32_16x16x32_bf16 v[58:61], v[142:145], v[166:169], v[58:61]
	v_mfma_f32_16x16x32_bf16 v[42:45], v[138:141], v[170:173], v[42:45]
	v_mfma_f32_16x16x32_bf16 v[42:45], v[142:145], v[174:177], v[42:45]
	v_mfma_f32_16x16x32_bf16 v[26:29], v[138:141], v[178:181], v[26:29]
	v_mfma_f32_16x16x32_bf16 v[26:29], v[142:145], v[182:185], v[26:29]
	v_mfma_f32_16x16x32_bf16 v[10:13], v[138:141], v[186:189], v[10:13]
	v_mfma_f32_16x16x32_bf16 v[10:13], v[142:145], v[190:193], v[10:13]
	s_setprio 0
	s_setprio 1
	v_mfma_f32_16x16x32_bf16 v[54:57], v[146:149], v[162:165], v[54:57]
	v_mfma_f32_16x16x32_bf16 v[54:57], v[150:153], v[166:169], v[54:57]
	v_mfma_f32_16x16x32_bf16 v[38:41], v[146:149], v[170:173], v[38:41]
	v_mfma_f32_16x16x32_bf16 v[38:41], v[150:153], v[174:177], v[38:41]
	v_mfma_f32_16x16x32_bf16 v[22:25], v[146:149], v[178:181], v[22:25]
	v_mfma_f32_16x16x32_bf16 v[22:25], v[150:153], v[182:185], v[22:25]
	v_mfma_f32_16x16x32_bf16 v[6:9], v[146:149], v[186:189], v[6:9]
	v_mfma_f32_16x16x32_bf16 v[6:9], v[150:153], v[190:193], v[6:9]
	v_mfma_f32_16x16x32_bf16 v[50:53], v[154:157], v[162:165], v[50:53]
	v_mfma_f32_16x16x32_bf16 v[50:53], v[158:161], v[166:169], v[50:53]
	v_mfma_f32_16x16x32_bf16 v[34:37], v[154:157], v[170:173], v[34:37]
	v_mfma_f32_16x16x32_bf16 v[34:37], v[158:161], v[174:177], v[34:37]
	v_mfma_f32_16x16x32_bf16 v[18:21], v[154:157], v[178:181], v[18:21]
	v_mfma_f32_16x16x32_bf16 v[18:21], v[158:161], v[182:185], v[18:21]
	v_mfma_f32_16x16x32_bf16 v[2:5], v[154:157], v[186:189], v[2:5]
	v_mfma_f32_16x16x32_bf16 v[2:5], v[158:161], v[190:193], v[2:5]
	s_setprio 0
	s_barrier
	s_add_u32 s48, s48, 0x100
	s_addc_u32 s49, s49, 0
	s_add_u32 s50, s50, 0x100
	s_addc_u32 s51, s51, 0
	s_cmp_ge_u32 vcc_lo, s96
	s_mov_b32 s46, vcc_lo
	s_cbranch_scc0 .LBB0_274
	s_and_b64 vcc, exec, s[72:73]
	s_cbranch_vccz .LBB0_277
	s_barrier

; #define PG8_STAGE(bufoff, gbase, voff) do { _Pragma("unroll") for (int _i = 0; _i < 2; ++_i) \
;         __builtin_amdgcn_global_load_lds((const unsigned*)((const char*)(gbase) + (voff)[_i]), (PG8_LAS unsigned*)(lds + (bufoff) + ldsw + _i * 8192), 16, 0, 0); } while (0)
; #define PG8_LDA(dst, b, h) do { _Pragma("unroll") for (int m = 0; m < 4; ++m) _Pragma("unroll") for (int k = 0; k < 2; ++k) dst[m][k] = *(const PG8_LAS bf16x8*)(lds + PG8_SA(b, h) + aoff + m * 2048 + k * 1024); } while (0)
; #define PG8_LDB(dst, b, h) do { _Pragma("unroll") for (int n = 0; n < 2; ++n) _Pragma("unroll") for (int k = 0; k < 2; ++k) dst[n][k] = *(const PG8_LAS bf16x8*)(lds + PG8_SB(b, h) + boff + n * 2048 + k * 1024); } while (0)
; #define PG8_MMA(ai, bj, At, Bt) do { __builtin_amdgcn_s_setprio(1); _Pragma("unroll") for (int m = 0; m < 4; ++m) _Pragma("unroll") for (int n = 0; n < 2; ++n) _Pragma("unroll") for (int k = 0; k < 2; ++k) \
;         acc[ai][bj][m][n] = __builtin_amdgcn_mfma_f32_16x16x32_bf16(Bt[n][k], At[m][k], acc[ai][bj][m][n], 0, 0, 0); __builtin_amdgcn_s_setprio(0); } while (0)
; #define PG8_WAIT_V(n) asm volatile("s_waitcnt vmcnt(" #n ")" ::: "memory")
; #define PG8_WAIT_L(n) asm volatile("s_waitcnt lgkmcnt(" #n ")" ::: "memory")
; #define PG8_BAR __builtin_amdgcn_s_barrier()
; #define PG8_SCHED __builtin_amdgcn_sched_barrier(0)
; template <class Epi, class Sched, bool ALIGN_EPI = false, bool SP2 = false>
; __device__ __forceinline__ void gemm_phase(PG8_LAS unsigned char* lds, const Gemm g, const Sched& S, const Epi& E) {
;     ...
;         for (int t = 0; t < nt; t += 2) {
;             const bool last = (t == nt - 2);
;             const char* a1 = cA + (size_t)(t + 1) * kstep;
;             const char* a2 = last ? nA : cA + (size_t)(t + 2) * kstep; const char* b2 = last ? nB : cB + (size_t)(t + 2) * kstep;
;             const char* a3 = a2 + kstep; const char* b3 = b2 + kstep;
;             if (last && has_next) S.a_ready(nxt);
;             if constexpr (SP2) {
;             PG8_LDB(B0, 0, 0); PG8_LDB(B1, 0, 1); PG8_SCHED; PG8_LDA(At, 0, 0); PG8_STAGE(PG8_SA(1, 1), a1 + hstep, voffA);
;             PG8_WAIT_V(8); PG8_WAIT_L(0); PG8_BAR; PG8_MMA(0, 0, At, B0); PG8_MMA(0, 1, At, B1); PG8_BAR; PG8_SCHED;
;             PG8_LDA(At, 0, 1); PG8_STAGE(PG8_SB(0, 0), b2, voffB); PG8_STAGE(PG8_SB(0, 1), b2 + hstep, voffB); PG8_STAGE(PG8_SA(0, 0), a2, voffA);
.LBB0_408:
	s_add_u32 s38, s48, 0xfffc0080
	s_addc_u32 s39, s49, -1
	s_add_i32 s85, 0, 0x10000
	s_cmp_eq_u32 s84, 12
	s_cselect_b32 s73, s21, s39
	s_cselect_b32 s72, s27, s38
	v_add_u32_e32 v0, s85, v167
	s_cselect_b32 s47, s29, s69
	s_cselect_b32 s46, s33, s53
	s_add_i32 s38, 0, 0x14000
	ds_read_b128 v[142:145], v0
	ds_read_b128 v[146:149], v0 offset:1024
	ds_read_b128 v[150:153], v0 offset:2048
	ds_read_b128 v[154:157], v0 offset:3072
	v_add_u32_e32 v0, s38, v167
	ds_read_b128 v[158:161], v0
	ds_read_b128 v[162:165], v0 offset:1024
	ds_read_b128 v[172:175], v0 offset:2048
	ds_read_b128 v[176:179], v0 offset:3072
	v_lshl_add_u64 v[218:219], s[48:49], 0, v[138:139]
	s_add_i32 m0, s76, 0xc000
	ds_read_b128 v[180:183], v170
	ds_read_b128 v[184:187], v170 offset:1024
	ds_read_b128 v[188:191], v170 offset:2048
	ds_read_b128 v[192:195], v170 offset:3072
	ds_read_b128 v[202:205], v170 offset:4096
	ds_read_b128 v[206:209], v170 offset:5120
	ds_read_b128 v[210:213], v170 offset:6144
	ds_read_b128 v[214:217], v170 offset:7168
	global_load_lds_dwordx4 v[218:219], off
	v_lshl_add_u64 v[218:219], s[48:49], 0, v[140:141]
	s_add_i32 m0, s76, 0xe000
	s_nop 0
	global_load_lds_dwordx4 v[218:219], off
	s_waitcnt vmcnt(8)
	s_waitcnt lgkmcnt(0)
	s_barrier
	s_setprio 1
	s_waitcnt lgkmcnt(0)
	v_mfma_f32_16x16x32_bf16 v[122:125], v[142:145], v[180:183], v[122:125]
	v_mfma_f32_16x16x32_bf16 v[122:125], v[146:149], v[184:187], v[122:125]
	v_mfma_f32_16x16x32_bf16 v[106:109], v[142:145], v[188:191], v[106:109]
	v_mfma_f32_16x16x32_bf16 v[106:109], v[146:149], v[192:195], v[106:109]
	v_mfma_f32_16x16x32_bf16 v[90:93], v[142:145], v[202:205], v[90:93]
	v_mfma_f32_16x16x32_bf16 v[90:93], v[146:149], v[206:209], v[90:93]
	v_mfma_f32_16x16x32_bf16 v[74:77], v[142:145], v[210:213], v[74:77]
	v_mfma_f32_16x16x32_bf16 v[74:77], v[146:149], v[214:217], v[74:77]
	v_mfma_f32_16x16x32_bf16 v[126:129], v[150:153], v[180:183], v[126:129]
	v_mfma_f32_16x16x32_bf16 v[126:129], v[154:157], v[184:187], v[126:129]
	v_mfma_f32_16x16x32_bf16 v[110:113], v[150:153], v[188:191], v[110:113]
	v_mfma_f32_16x16x32_bf16 v[110:113], v[154:157], v[192:195], v[110:113]
	v_mfma_f32_16x16x32_bf16 v[94:97], v[150:153], v[202:205], v[94:97]
	v_mfma_f32_16x16x32_bf16 v[94:97], v[154:157], v[206:209], v[94:97]
	v_mfma_f32_16x16x32_bf16 v[78:81], v[150:153], v[210:213], v[78:81]
	v_mfma_f32_16x16x32_bf16 v[78:81], v[154:157], v[214:217], v[78:81]
	s_setprio 0
	s_setprio 1
	v_mfma_f32_16x16x32_bf16 v[114:117], v[158:161], v[180:183], v[114:117]
	v_mfma_f32_16x16x32_bf16 v[114:117], v[162:165], v[184:187], v[114:117]
	v_mfma_f32_16x16x32_bf16 v[98:101], v[158:161], v[188:191], v[98:101]
	v_mfma_f32_16x16x32_bf16 v[98:101], v[162:165], v[192:195], v[98:101]
	v_mfma_f32_16x16x32_bf16 v[82:85], v[158:161], v[202:205], v[82:85]
	v_mfma_f32_16x16x32_bf16 v[82:85], v[162:165], v[206:209], v[82:85]
	v_mfma_f32_16x16x32_bf16 v[66:69], v[158:161], v[210:213], v[66:69]
	v_mfma_f32_16x16x32_bf16 v[66:69], v[162:165], v[214:217], v[66:69]
	v_mfma_f32_16x16x32_bf16 v[118:121], v[172:175], v[180:183], v[118:121]
	v_mfma_f32_16x16x32_bf16 v[118:121], v[176:179], v[184:187], v[118:121]
	v_mfma_f32_16x16x32_bf16 v[102:105], v[172:175], v[188:191], v[102:105]
	v_mfma_f32_16x16x32_bf16 v[102:105], v[176:179], v[192:195], v[102:105]
	v_mfma_f32_16x16x32_bf16 v[86:89], v[172:175], v[202:205], v[86:89]
	v_mfma_f32_16x16x32_bf16 v[86:89], v[176:179], v[206:209], v[86:89]
	v_mfma_f32_16x16x32_bf16 v[70:73], v[172:175], v[210:213], v[70:73]
	v_mfma_f32_16x16x32_bf16 v[70:73], v[176:179], v[214:217], v[70:73]
	s_setprio 0
	s_barrier
	s_add_i32 s39, s85, s75
	v_lshl_add_u64 v[218:219], s[46:47], 0, v[134:135]
	s_mov_b32 m0, s39
	ds_read_b128 v[180:183], v170 offset:16384
	ds_read_b128 v[184:187], v170 offset:17408
	ds_read_b128 v[188:191], v170 offset:18432
	ds_read_b128 v[192:195], v170 offset:19456
	ds_read_b128 v[202:205], v170 offset:20480
	ds_read_b128 v[206:209], v170 offset:21504
	ds_read_b128 v[210:213], v170 offset:22528
	ds_read_b128 v[214:217], v170 offset:23552
	global_load_lds_dwordx4 v[218:219], off
	s_add_i32 m0, s39, 0x2000
	s_add_u32 s92, s46, 0x40000
	v_lshl_add_u64 v[220:221], s[46:47], 0, v[130:131]
	s_addc_u32 s93, s47, 0
	s_add_i32 s38, s38, s75
	global_load_lds_dwordx4 v[220:221], off
	v_lshl_add_u64 v[222:223], s[92:93], 0, v[134:135]
	s_mov_b32 m0, s38
	v_lshl_add_u64 v[224:225], s[72:73], 0, v[132:133]
	global_load_lds_dwordx4 v[222:223], off
	v_lshl_add_u64 v[222:223], s[92:93], 0, v[130:131]
	s_add_i32 m0, s38, 0x2000
	s_nop 0
	global_load_lds_dwordx4 v[222:223], off
	v_lshl_add_u64 v[222:223], s[72:73], 0, v[136:137]
	s_mov_b32 m0, s76
	s_nop 0
	global_load_lds_dwordx4 v[222:223], off
	s_mov_b32 m0, s77
	s_nop 0
	global_load_lds_dwordx4 v[224:225], off
	s_waitcnt vmcnt(8)
	s_waitcnt lgkmcnt(0)
	s_barrier
; #define PG8_STAGE(bufoff, gbase, voff) do { _Pragma("unroll") for (int _i = 0; _i < 2; ++_i) \
;         __builtin_amdgcn_global_load_lds((const unsigned*)((const char*)(gbase) + (voff)[_i]), (PG8_LAS unsigned*)(lds + (bufoff) + ldsw + _i * 8192), 16, 0, 0); } while (0)
; #define PG8_LDA(dst, b, h) do { _Pragma("unroll") for (int m = 0; m < 4; ++m) _Pragma("unroll") for (int k = 0; k < 2; ++k) dst[m][k] = *(const PG8_LAS bf16x8*)(lds + PG8_SA(b, h) + aoff + m * 2048 + k * 1024); } while (0)
; #define PG8_LDB(dst, b, h) do { _Pragma("unroll") for (int n = 0; n < 2; ++n) _Pragma("unroll") for (int k = 0; k < 2; ++k) dst[n][k] = *(const PG8_LAS bf16x8*)(lds + PG8_SB(b, h) + boff + n * 2048 + k * 1024); } while (0)
; #define PG8_MMA(ai, bj, At, Bt) do { __builtin_amdgcn_s_setprio(1); _Pragma("unroll") for (int m = 0; m < 4; ++m) _Pragma("unroll") for (int n = 0; n < 2; ++n) _Pragma("unroll") for (int k = 0; k < 2; ++k) \
;         acc[ai][bj][m][n] = __builtin_amdgcn_mfma_f32_16x16x32_bf16(Bt[n][k], At[m][k], acc[ai][bj][m][n], 0, 0, 0); __builtin_amdgcn_s_setprio(0); } while (0)
; #define PG8_WAIT_V(n) asm volatile("s_waitcnt vmcnt(" #n ")" ::: "memory")
; #define PG8_WAIT_L(n) asm volatile("s_waitcnt lgkmcnt(" #n ")" ::: "memory")
; #define PG8_BAR __builtin_amdgcn_s_barrier()
; #define PG8_SCHED __builtin_amdgcn_sched_barrier(0)
; template <class Epi, class Sched, bool ALIGN_EPI = false, bool SP2 = false>
; __device__ __forceinline__ void gemm_phase(PG8_LAS unsigned char* lds, const Gemm g, const Sched& S, const Epi& E) {
;     ...
;             PG8_WAIT_V(8); PG8_WAIT_L(0); PG8_BAR; PG8_MMA(1, 0, At, B0); PG8_MMA(1, 1, At, B1); PG8_BAR; PG8_SCHED;
;             PG8_LDB(B0, 1, 0); PG8_LDB(B1, 1, 1); PG8_SCHED; PG8_LDA(At, 1, 0); PG8_STAGE(PG8_SA(0, 1), a2 + hstep, voffA);
;             PG8_WAIT_V(8); PG8_WAIT_L(0); PG8_BAR; PG8_MMA(0, 0, At, B0); PG8_MMA(0, 1, At, B1); PG8_BAR; PG8_SCHED;
	s_setprio 1
	s_waitcnt lgkmcnt(0)
	v_mfma_f32_16x16x32_bf16 v[58:61], v[142:145], v[180:183], v[58:61]
	v_mfma_f32_16x16x32_bf16 v[58:61], v[146:149], v[184:187], v[58:61]
	v_mfma_f32_16x16x32_bf16 v[42:45], v[142:145], v[188:191], v[42:45]
	v_mfma_f32_16x16x32_bf16 v[42:45], v[146:149], v[192:195], v[42:45]
	v_mfma_f32_16x16x32_bf16 v[26:29], v[142:145], v[202:205], v[26:29]
	v_mfma_f32_16x16x32_bf16 v[26:29], v[146:149], v[206:209], v[26:29]
	v_mfma_f32_16x16x32_bf16 v[10:13], v[142:145], v[210:213], v[10:13]
	v_mfma_f32_16x16x32_bf16 v[10:13], v[146:149], v[214:217], v[10:13]
	v_mfma_f32_16x16x32_bf16 v[62:65], v[150:153], v[180:183], v[62:65]
	v_mfma_f32_16x16x32_bf16 v[62:65], v[154:157], v[184:187], v[62:65]
	v_mfma_f32_16x16x32_bf16 v[46:49], v[150:153], v[188:191], v[46:49]
	v_mfma_f32_16x16x32_bf16 v[46:49], v[154:157], v[192:195], v[46:49]
	v_mfma_f32_16x16x32_bf16 v[30:33], v[150:153], v[202:205], v[30:33]
	v_mfma_f32_16x16x32_bf16 v[30:33], v[154:157], v[206:209], v[30:33]
	v_mfma_f32_16x16x32_bf16 v[14:17], v[150:153], v[210:213], v[14:17]
	v_mfma_f32_16x16x32_bf16 v[14:17], v[154:157], v[214:217], v[14:17]
	s_setprio 0
	s_setprio 1
	v_mfma_f32_16x16x32_bf16 v[50:53], v[158:161], v[180:183], v[50:53]
	v_mfma_f32_16x16x32_bf16 v[50:53], v[162:165], v[184:187], v[50:53]
	v_mfma_f32_16x16x32_bf16 v[34:37], v[158:161], v[188:191], v[34:37]
	v_mfma_f32_16x16x32_bf16 v[34:37], v[162:165], v[192:195], v[34:37]
	v_mfma_f32_16x16x32_bf16 v[18:21], v[158:161], v[202:205], v[18:21]
	v_mfma_f32_16x16x32_bf16 v[18:21], v[162:165], v[206:209], v[18:21]
	v_mfma_f32_16x16x32_bf16 v[2:5], v[158:161], v[210:213], v[2:5]
	v_mfma_f32_16x16x32_bf16 v[2:5], v[162:165], v[214:217], v[2:5]
	v_mfma_f32_16x16x32_bf16 v[54:57], v[172:175], v[180:183], v[54:57]
	v_mfma_f32_16x16x32_bf16 v[54:57], v[176:179], v[184:187], v[54:57]
	v_mfma_f32_16x16x32_bf16 v[38:41], v[172:175], v[188:191], v[38:41]
	v_mfma_f32_16x16x32_bf16 v[38:41], v[176:179], v[192:195], v[38:41]
	v_mfma_f32_16x16x32_bf16 v[22:25], v[172:175], v[202:205], v[22:25]
	v_mfma_f32_16x16x32_bf16 v[22:25], v[176:179], v[206:209], v[22:25]
	v_mfma_f32_16x16x32_bf16 v[6:9], v[172:175], v[210:213], v[6:9]
	v_mfma_f32_16x16x32_bf16 v[6:9], v[176:179], v[214:217], v[6:9]
	s_setprio 0
	s_barrier
	s_add_i32 s38, 0, 0x18000
	v_add_u32_e32 v0, s38, v167
	s_add_i32 s39, 0, 0x1c000
	ds_read_b128 v[142:145], v0
	ds_read_b128 v[146:149], v0 offset:1024
	ds_read_b128 v[150:153], v0 offset:2048
	ds_read_b128 v[154:157], v0 offset:3072
	v_add_u32_e32 v0, s39, v167
	ds_read_b128 v[158:161], v0
	ds_read_b128 v[162:165], v0 offset:1024
	ds_read_b128 v[172:175], v0 offset:2048
	ds_read_b128 v[176:179], v0 offset:3072
	s_add_u32 s72, s72, 0x40000
	s_addc_u32 s73, s73, 0
	s_mov_b32 m0, s78
	v_lshl_add_u64 v[226:227], s[72:73], 0, v[136:137]
	ds_read_b128 v[180:183], v170 offset:32768
	ds_read_b128 v[184:187], v170 offset:33792
	ds_read_b128 v[188:191], v170 offset:34816
	ds_read_b128 v[192:195], v170 offset:35840
	ds_read_b128 v[202:205], v170 offset:36864
	ds_read_b128 v[206:209], v170 offset:37888
	ds_read_b128 v[210:213], v170 offset:38912
	ds_read_b128 v[214:217], v170 offset:39936
	global_load_lds_dwordx4 v[226:227], off
	v_lshl_add_u64 v[226:227], s[72:73], 0, v[132:133]
	s_mov_b32 m0, s79
	s_nop 0
	global_load_lds_dwordx4 v[226:227], off
	s_waitcnt vmcnt(8)
	s_waitcnt lgkmcnt(0)
	s_barrier
	s_setprio 1
	s_waitcnt lgkmcnt(0)
	v_mfma_f32_16x16x32_bf16 v[122:125], v[142:145], v[180:183], v[122:125]
	v_mfma_f32_16x16x32_bf16 v[122:125], v[146:149], v[184:187], v[122:125]
	v_mfma_f32_16x16x32_bf16 v[106:109], v[142:145], v[188:191], v[106:109]
	v_mfma_f32_16x16x32_bf16 v[106:109], v[146:149], v[192:195], v[106:109]
	v_mfma_f32_16x16x32_bf16 v[90:93], v[142:145], v[202:205], v[90:93]
	v_mfma_f32_16x16x32_bf16 v[90:93], v[146:149], v[206:209], v[90:93]
	v_mfma_f32_16x16x32_bf16 v[74:77], v[142:145], v[210:213], v[74:77]
	v_mfma_f32_16x16x32_bf16 v[74:77], v[146:149], v[214:217], v[74:77]
	v_mfma_f32_16x16x32_bf16 v[126:129], v[150:153], v[180:183], v[126:129]
	v_mfma_f32_16x16x32_bf16 v[126:129], v[154:157], v[184:187], v[126:129]
	v_mfma_f32_16x16x32_bf16 v[110:113], v[150:153], v[188:191], v[110:113]
	v_mfma_f32_16x16x32_bf16 v[110:113], v[154:157], v[192:195], v[110:113]
	v_mfma_f32_16x16x32_bf16 v[94:97], v[150:153], v[202:205], v[94:97]
	v_mfma_f32_16x16x32_bf16 v[94:97], v[154:157], v[206:209], v[94:97]
	v_mfma_f32_16x16x32_bf16 v[78:81], v[150:153], v[210:213], v[78:81]
	v_mfma_f32_16x16x32_bf16 v[78:81], v[154:157], v[214:217], v[78:81]
	s_setprio 0
	s_setprio 1
	v_mfma_f32_16x16x32_bf16 v[114:117], v[158:161], v[180:183], v[114:117]
	v_mfma_f32_16x16x32_bf16 v[114:117], v[162:165], v[184:187], v[114:117]
	v_mfma_f32_16x16x32_bf16 v[98:101], v[158:161], v[188:191], v[98:101]
	v_mfma_f32_16x16x32_bf16 v[98:101], v[162:165], v[192:195], v[98:101]
	v_mfma_f32_16x16x32_bf16 v[82:85], v[158:161], v[202:205], v[82:85]
	v_mfma_f32_16x16x32_bf16 v[82:85], v[162:165], v[206:209], v[82:85]
	v_mfma_f32_16x16x32_bf16 v[66:69], v[158:161], v[210:213], v[66:69]
	v_mfma_f32_16x16x32_bf16 v[66:69], v[162:165], v[214:217], v[66:69]
	v_mfma_f32_16x16x32_bf16 v[118:121], v[172:175], v[180:183], v[118:121]
	v_mfma_f32_16x16x32_bf16 v[118:121], v[176:179], v[184:187], v[118:121]
	v_mfma_f32_16x16x32_bf16 v[102:105], v[172:175], v[188:191], v[102:105]
	v_mfma_f32_16x16x32_bf16 v[102:105], v[176:179], v[192:195], v[102:105]
	v_mfma_f32_16x16x32_bf16 v[86:89], v[172:175], v[202:205], v[86:89]
	v_mfma_f32_16x16x32_bf16 v[86:89], v[176:179], v[206:209], v[86:89]
	v_mfma_f32_16x16x32_bf16 v[70:73], v[172:175], v[210:213], v[70:73]
	v_mfma_f32_16x16x32_bf16 v[70:73], v[176:179], v[214:217], v[70:73]
	s_setprio 0
	s_barrier
; #define PG8_STAGE(bufoff, gbase, voff) do { _Pragma("unroll") for (int _i = 0; _i < 2; ++_i) \
;         __builtin_amdgcn_global_load_lds((const unsigned*)((const char*)(gbase) + (voff)[_i]), (PG8_LAS unsigned*)(lds + (bufoff) + ldsw + _i * 8192), 16, 0, 0); } while (0)
; #define PG8_LDA(dst, b, h) do { _Pragma("unroll") for (int m = 0; m < 4; ++m) _Pragma("unroll") for (int k = 0; k < 2; ++k) dst[m][k] = *(const PG8_LAS bf16x8*)(lds + PG8_SA(b, h) + aoff + m * 2048 + k * 1024); } while (0)
; #define PG8_LDB(dst, b, h) do { _Pragma("unroll") for (int n = 0; n < 2; ++n) _Pragma("unroll") for (int k = 0; k < 2; ++k) dst[n][k] = *(const PG8_LAS bf16x8*)(lds + PG8_SB(b, h) + boff + n * 2048 + k * 1024); } while (0)
; template <class Epi, class Sched, bool ALIGN_EPI = false, bool SP2 = false>
; __device__ __forceinline__ void gemm_phase(PG8_LAS unsigned char* lds, const Gemm g, const Sched& S, const Epi& E) {
;     ...
;         for (int t = 0; t < nt; t += 2) {
;             const bool last = (t == nt - 2);
;             const char* a1 = cA + (size_t)(t + 1) * kstep;
;             const char* a2 = last ? nA : cA + (size_t)(t + 2) * kstep; const char* b2 = last ? nB : cB + (size_t)(t + 2) * kstep;
;             const char* a3 = a2 + kstep; const char* b3 = b2 + kstep;
;             if (last && has_next) S.a_ready(nxt);
;             if constexpr (SP2) {
;             PG8_LDB(B0, 0, 0); PG8_LDB(B1, 0, 1); PG8_SCHED; PG8_LDA(At, 0, 0); PG8_STAGE(PG8_SA(1, 1), a1 + hstep, voffA);
;             PG8_WAIT_V(8); PG8_WAIT_L(0); PG8_BAR; PG8_MMA(0, 0, At, B0); PG8_MMA(0, 1, At, B1); PG8_BAR; PG8_SCHED;
;             PG8_LDA(At, 0, 1); PG8_STAGE(PG8_SB(0, 0), b2, voffB); PG8_STAGE(PG8_SB(0, 1), b2 + hstep, voffB); PG8_STAGE(PG8_SA(0, 0), a2, voffA);
;             PG8_WAIT_V(8); PG8_WAIT_L(0); PG8_BAR; PG8_MMA(1, 0, At, B0); PG8_MMA(1, 1, At, B1); PG8_BAR; PG8_SCHED;
;             PG8_LDB(B0, 1, 0); PG8_LDB(B1, 1, 1); PG8_SCHED; PG8_LDA(At, 1, 0); PG8_STAGE(PG8_SA(0, 1), a2 + hstep, voffA);
;             PG8_WAIT_V(8); PG8_WAIT_L(0); PG8_BAR; PG8_MMA(0, 0, At, B0); PG8_MMA(0, 1, At, B1); PG8_BAR; PG8_SCHED;
;             PG8_LDA(At, 1, 1); PG8_STAGE(PG8_SB(1, 0), b3, voffB); PG8_STAGE(PG8_SB(1, 1), b3 + hstep, voffB); PG8_STAGE(PG8_SA(1, 0), a3, voffA);
;             PG8_WAIT_V(8); PG8_WAIT_L(0); PG8_BAR; PG8_MMA(1, 0, At, B0); PG8_MMA(1, 1, At, B1); PG8_BAR; PG8_SCHED;
	s_add_i32 s38, s38, s75
	v_lshl_add_u64 v[218:219], v[218:219], 0, s[30:31]
	s_mov_b32 m0, s38
	ds_read_b128 v[180:183], v170 offset:49152
	ds_read_b128 v[184:187], v170 offset:50176
	ds_read_b128 v[188:191], v170 offset:51200
	ds_read_b128 v[192:195], v170 offset:52224
	ds_read_b128 v[202:205], v170 offset:53248
	ds_read_b128 v[206:209], v170 offset:54272
	ds_read_b128 v[210:213], v170 offset:55296
	ds_read_b128 v[214:217], v170 offset:56320
	global_load_lds_dwordx4 v[218:219], off
	s_add_i32 m0, s38, 0x2000
	s_add_u32 s46, s46, 0x40080
	v_lshl_add_u64 v[218:219], v[220:221], 0, s[30:31]
	s_addc_u32 s47, s47, 0
	s_add_i32 s38, s39, s75
	global_load_lds_dwordx4 v[218:219], off
	v_lshl_add_u64 v[218:219], s[46:47], 0, v[134:135]
	s_mov_b32 m0, s38
	s_nop 0
	global_load_lds_dwordx4 v[218:219], off
	v_lshl_add_u64 v[218:219], s[46:47], 0, v[130:131]
	s_add_i32 m0, s38, 0x2000
	s_nop 0
	global_load_lds_dwordx4 v[218:219], off
	v_lshl_add_u64 v[218:219], v[222:223], 0, s[30:31]
	s_mov_b32 m0, s80
	s_nop 0
	global_load_lds_dwordx4 v[218:219], off
	v_lshl_add_u64 v[218:219], v[224:225], 0, s[30:31]
	s_mov_b32 m0, s81
	s_nop 0
	global_load_lds_dwordx4 v[218:219], off
	s_waitcnt vmcnt(8)
	s_waitcnt lgkmcnt(0)
	s_barrier
	s_setprio 1
	s_waitcnt lgkmcnt(0)
	v_mfma_f32_16x16x32_bf16 v[58:61], v[142:145], v[180:183], v[58:61]
	v_mfma_f32_16x16x32_bf16 v[58:61], v[146:149], v[184:187], v[58:61]
	v_mfma_f32_16x16x32_bf16 v[42:45], v[142:145], v[188:191], v[42:45]
	v_mfma_f32_16x16x32_bf16 v[42:45], v[146:149], v[192:195], v[42:45]
	v_mfma_f32_16x16x32_bf16 v[26:29], v[142:145], v[202:205], v[26:29]
	v_mfma_f32_16x16x32_bf16 v[26:29], v[146:149], v[206:209], v[26:29]
	v_mfma_f32_16x16x32_bf16 v[10:13], v[142:145], v[210:213], v[10:13]
	v_mfma_f32_16x16x32_bf16 v[10:13], v[146:149], v[214:217], v[10:13]
	v_mfma_f32_16x16x32_bf16 v[62:65], v[150:153], v[180:183], v[62:65]
	v_mfma_f32_16x16x32_bf16 v[62:65], v[154:157], v[184:187], v[62:65]
	v_mfma_f32_16x16x32_bf16 v[46:49], v[150:153], v[188:191], v[46:49]
	v_mfma_f32_16x16x32_bf16 v[46:49], v[154:157], v[192:195], v[46:49]
	v_mfma_f32_16x16x32_bf16 v[30:33], v[150:153], v[202:205], v[30:33]
	v_mfma_f32_16x16x32_bf16 v[30:33], v[154:157], v[206:209], v[30:33]
	v_mfma_f32_16x16x32_bf16 v[14:17], v[150:153], v[210:213], v[14:17]
	v_mfma_f32_16x16x32_bf16 v[14:17], v[154:157], v[214:217], v[14:17]
	s_setprio 0
	s_setprio 1
	v_mfma_f32_16x16x32_bf16 v[50:53], v[158:161], v[180:183], v[50:53]
	v_mfma_f32_16x16x32_bf16 v[50:53], v[162:165], v[184:187], v[50:53]
	v_mfma_f32_16x16x32_bf16 v[34:37], v[158:161], v[188:191], v[34:37]
	v_mfma_f32_16x16x32_bf16 v[34:37], v[162:165], v[192:195], v[34:37]
	v_mfma_f32_16x16x32_bf16 v[18:21], v[158:161], v[202:205], v[18:21]
	v_mfma_f32_16x16x32_bf16 v[18:21], v[162:165], v[206:209], v[18:21]
	v_mfma_f32_16x16x32_bf16 v[2:5], v[158:161], v[210:213], v[2:5]
	v_mfma_f32_16x16x32_bf16 v[2:5], v[162:165], v[214:217], v[2:5]
	v_mfma_f32_16x16x32_bf16 v[54:57], v[172:175], v[180:183], v[54:57]
	v_mfma_f32_16x16x32_bf16 v[54:57], v[176:179], v[184:187], v[54:57]
	v_mfma_f32_16x16x32_bf16 v[38:41], v[172:175], v[188:191], v[38:41]
	v_mfma_f32_16x16x32_bf16 v[38:41], v[176:179], v[192:195], v[38:41]
	v_mfma_f32_16x16x32_bf16 v[22:25], v[172:175], v[202:205], v[22:25]
	v_mfma_f32_16x16x32_bf16 v[22:25], v[176:179], v[206:209], v[22:25]
	v_mfma_f32_16x16x32_bf16 v[6:9], v[172:175], v[210:213], v[6:9]
	v_mfma_f32_16x16x32_bf16 v[6:9], v[176:179], v[214:217], v[6:9]
	s_setprio 0
	s_barrier
	s_add_i32 s84, s84, 2
	s_add_u32 s48, s48, 0x100
	s_addc_u32 s49, s49, 0
	s_add_u32 s53, s53, 0x100
	s_addc_u32 s69, s69, 0
	s_cmp_gt_u32 s84, 13
	s_cbranch_scc0 .LBB0_408
	s_and_b64 vcc, exec, s[64:65]
	s_cbranch_vccz .LBB0_411
	s_barrier
